# GEMM K-loops: priority raised for the LOADING wave (setprio 1 after compute-closing barrier, 0 before load-closing barrier) instead of the computing wave
# baseline (speedup 1.0000x reference)
; #define PG8_STAGE(bufoff, gbase, voff) do { _Pragma("unroll") for (int _i = 0; _i < 2; ++_i) \
;         __builtin_amdgcn_global_load_lds((const unsigned*)((const char*)(gbase) + (voff)[_i]), (PG8_LAS unsigned*)(lds + (bufoff) + ldsw + _i * 8192), 16, 0, 0); } while (0)
; #define PG8_LDA(dst, b, h) do { _Pragma("unroll") for (int m = 0; m < 4; ++m) _Pragma("unroll") for (int k = 0; k < 2; ++k) dst[m][k] = *(const PG8_LAS bf16x8*)(lds + PG8_SA(b, h) + aoff + m * 2048 + k * 1024); } while (0)
; #define PG8_LDB(dst, b, h) do { _Pragma("unroll") for (int n = 0; n < 2; ++n) _Pragma("unroll") for (int k = 0; k < 2; ++k) dst[n][k] = *(const PG8_LAS bf16x8*)(lds + PG8_SB(b, h) + boff + n * 2048 + k * 1024); } while (0)
; #define PG8_MMA(ai, bj, At, Bt) do { __builtin_amdgcn_s_setprio(1); _Pragma("unroll") for (int m = 0; m < 4; ++m) _Pragma("unroll") for (int n = 0; n < 2; ++n) _Pragma("unroll") for (int k = 0; k < 2; ++k) \
;         acc[ai][bj][m][n] = __builtin_amdgcn_mfma_f32_16x16x32_bf16(Bt[n][k], At[m][k], acc[ai][bj][m][n], 0, 0, 0); __builtin_amdgcn_s_setprio(0); } while (0)
; #define PG8_WAIT_V(n) asm volatile("s_waitcnt vmcnt(" #n ")" ::: "memory")
; #define PG8_WAIT_L(n) asm volatile("s_waitcnt lgkmcnt(" #n ")" ::: "memory")
; template <class Epi, class Sched, bool ALIGN_EPI = false, bool SP2 = false>
; __device__ __forceinline__ void gemm_phase(PG8_LAS unsigned char* lds, const Gemm g, const Sched& S, const Epi& E) {
;     ...
;             const bool last = (t == nt - 2);
;             const char* a1 = cA + (size_t)(t + 1) * kstep;
;             const char* a2 = last ? nA : cA + (size_t)(t + 2) * kstep; const char* b2 = last ? nB : cB + (size_t)(t + 2) * kstep;
;             const char* a3 = a2 + kstep; const char* b3 = b2 + kstep;
;             if (last && has_next) S.a_ready(nxt);
;             if constexpr (SP2) {
;             PG8_LDB(B0, 0, 0); PG8_LDB(B1, 0, 1); PG8_SCHED; PG8_LDA(At, 0, 0); PG8_STAGE(PG8_SA(1, 1), a1 + hstep, voffA);
;             PG8_WAIT_V(8); PG8_WAIT_L(0); PG8_BAR; PG8_MMA(0, 0, At, B0); PG8_MMA(0, 1, At, B1); PG8_BAR; PG8_SCHED;
;             PG8_LDA(At, 0, 1); PG8_STAGE(PG8_SB(0, 0), b2, voffB); PG8_STAGE(PG8_SB(0, 1), b2 + hstep, voffB); PG8_STAGE(PG8_SA(0, 0), a2, voffA);
;             PG8_WAIT_V(8); PG8_WAIT_L(0); PG8_BAR; PG8_MMA(1, 0, At, B0); PG8_MMA(1, 1, At, B1); PG8_BAR; PG8_SCHED;
.LBB0_265:
	s_add_u32 s10, s16, 0xfff80080
	s_addc_u32 s11, s17, -1
	s_add_i32 s27, 0, 0x10000
	s_cmp_eq_u32 s23, 28
	s_cselect_b32 s51, s5, s11
	s_cselect_b32 s50, s7, s10
	s_cselect_b32 s19, s8, s22
	s_cselect_b32 s18, s9, s15
	s_add_i32 s10, 0, 0x14000
	v_add_u32_e32 v168, s27, v157
	v_add_u32_e32 v184, s10, v157
	ds_read_b128 v[152:155], v168
	ds_read_b128 v[160:163], v168 offset:1024
	ds_read_b128 v[164:167], v168 offset:2048
	ds_read_b128 v[168:171], v168 offset:3072
	ds_read_b128 v[172:175], v184
	ds_read_b128 v[176:179], v184 offset:1024
	ds_read_b128 v[180:183], v184 offset:2048
	ds_read_b128 v[184:187], v184 offset:3072
	v_lshl_add_u64 v[200:201], s[16:17], 0, v[148:149]
	s_add_i32 m0, s57, 0xc000
	ds_read_b128 v[188:191], v159
	ds_read_b128 v[192:195], v159 offset:1024
	ds_read_b128 v[196:199], v159 offset:2048
	ds_read_b128 v[216:219], v159 offset:3072
	ds_read_b128 v[220:223], v159 offset:4096
	ds_read_b128 v[224:227], v159 offset:5120
	ds_read_b128 v[228:231], v159 offset:6144
	ds_read_b128 v[232:235], v159 offset:7168
	global_load_lds_dwordx4 v[200:201], off
	v_lshl_add_u64 v[200:201], s[16:17], 0, v[150:151]
	s_add_i32 m0, s57, 0xe000
	s_nop 0
	global_load_lds_dwordx4 v[200:201], off
	s_waitcnt vmcnt(8)
	s_waitcnt lgkmcnt(0)
	s_setprio 0
	s_barrier
	v_mfma_f32_16x16x32_bf16 v[126:129], v[152:155], v[188:191], v[126:129]
	v_mfma_f32_16x16x32_bf16 v[122:125], v[164:167], v[188:191], v[122:125]
	v_mfma_f32_16x16x32_bf16 v[110:113], v[152:155], v[196:199], v[110:113]
	v_mfma_f32_16x16x32_bf16 v[106:109], v[164:167], v[196:199], v[106:109]
	v_mfma_f32_16x16x32_bf16 v[94:97], v[152:155], v[220:223], v[94:97]
	v_mfma_f32_16x16x32_bf16 v[90:93], v[164:167], v[220:223], v[90:93]
	v_mfma_f32_16x16x32_bf16 v[78:81], v[152:155], v[228:231], v[78:81]
	v_mfma_f32_16x16x32_bf16 v[74:77], v[164:167], v[228:231], v[74:77]
	v_mfma_f32_16x16x32_bf16 v[126:129], v[160:163], v[192:195], v[126:129]
	v_mfma_f32_16x16x32_bf16 v[122:125], v[168:171], v[192:195], v[122:125]
	v_mfma_f32_16x16x32_bf16 v[110:113], v[160:163], v[216:219], v[110:113]
	v_mfma_f32_16x16x32_bf16 v[106:109], v[168:171], v[216:219], v[106:109]
	v_mfma_f32_16x16x32_bf16 v[94:97], v[160:163], v[224:227], v[94:97]
	v_mfma_f32_16x16x32_bf16 v[90:93], v[168:171], v[224:227], v[90:93]
	v_mfma_f32_16x16x32_bf16 v[78:81], v[160:163], v[232:235], v[78:81]
	v_mfma_f32_16x16x32_bf16 v[74:77], v[168:171], v[232:235], v[74:77]
	v_mfma_f32_16x16x32_bf16 v[118:121], v[172:175], v[188:191], v[118:121]
	v_mfma_f32_16x16x32_bf16 v[114:117], v[180:183], v[188:191], v[114:117]
	v_mfma_f32_16x16x32_bf16 v[102:105], v[172:175], v[196:199], v[102:105]
	v_mfma_f32_16x16x32_bf16 v[98:101], v[180:183], v[196:199], v[98:101]
	v_mfma_f32_16x16x32_bf16 v[86:89], v[172:175], v[220:223], v[86:89]
	v_mfma_f32_16x16x32_bf16 v[82:85], v[180:183], v[220:223], v[82:85]
	v_mfma_f32_16x16x32_bf16 v[70:73], v[172:175], v[228:231], v[70:73]
	v_mfma_f32_16x16x32_bf16 v[66:69], v[180:183], v[228:231], v[66:69]
	v_mfma_f32_16x16x32_bf16 v[118:121], v[176:179], v[192:195], v[118:121]
	v_mfma_f32_16x16x32_bf16 v[114:117], v[184:187], v[192:195], v[114:117]
	v_mfma_f32_16x16x32_bf16 v[102:105], v[176:179], v[216:219], v[102:105]
	v_mfma_f32_16x16x32_bf16 v[98:101], v[184:187], v[216:219], v[98:101]
	v_mfma_f32_16x16x32_bf16 v[86:89], v[176:179], v[224:227], v[86:89]
	v_mfma_f32_16x16x32_bf16 v[82:85], v[184:187], v[224:227], v[82:85]
	v_mfma_f32_16x16x32_bf16 v[70:73], v[176:179], v[232:235], v[70:73]
	v_mfma_f32_16x16x32_bf16 v[66:69], v[184:187], v[232:235], v[66:69]
	s_barrier
	s_setprio 1
	s_add_i32 s11, s27, s56
	v_lshl_add_u64 v[200:201], s[18:19], 0, v[0:1]
	s_mov_b32 m0, s11
	ds_read_b128 v[188:191], v159 offset:16384
	ds_read_b128 v[192:195], v159 offset:17408
	ds_read_b128 v[196:199], v159 offset:18432
	ds_read_b128 v[216:219], v159 offset:19456
	ds_read_b128 v[220:223], v159 offset:20480
	ds_read_b128 v[224:227], v159 offset:21504
	ds_read_b128 v[228:231], v159 offset:22528
	ds_read_b128 v[232:235], v159 offset:23552
	global_load_lds_dwordx4 v[200:201], off
	s_add_i32 m0, s11, 0x2000
	s_add_u32 s38, s18, 0x80000
	v_lshl_add_u64 v[236:237], s[18:19], 0, v[142:143]
	s_addc_u32 s39, s19, 0
	s_add_i32 s10, s10, s56
	global_load_lds_dwordx4 v[236:237], off
	v_lshl_add_u64 v[238:239], s[38:39], 0, v[0:1]
	s_mov_b32 m0, s10
	v_lshl_add_u64 v[240:241], s[50:51], 0, v[144:145]
	global_load_lds_dwordx4 v[238:239], off
	v_lshl_add_u64 v[238:239], s[38:39], 0, v[142:143]
	s_add_i32 m0, s10, 0x2000
	s_nop 0
	global_load_lds_dwordx4 v[238:239], off
	v_lshl_add_u64 v[238:239], s[50:51], 0, v[146:147]
	s_mov_b32 m0, s57
	s_nop 0
	global_load_lds_dwordx4 v[238:239], off
	s_mov_b32 m0, s58
	s_nop 0
	global_load_lds_dwordx4 v[240:241], off
	s_waitcnt vmcnt(8)
	s_waitcnt lgkmcnt(0)
	s_setprio 0
	s_barrier
; #define PG8_STAGE(bufoff, gbase, voff) do { _Pragma("unroll") for (int _i = 0; _i < 2; ++_i) \
;         __builtin_amdgcn_global_load_lds((const unsigned*)((const char*)(gbase) + (voff)[_i]), (PG8_LAS unsigned*)(lds + (bufoff) + ldsw + _i * 8192), 16, 0, 0); } while (0)
; #define PG8_LDA(dst, b, h) do { _Pragma("unroll") for (int m = 0; m < 4; ++m) _Pragma("unroll") for (int k = 0; k < 2; ++k) dst[m][k] = *(const PG8_LAS bf16x8*)(lds + PG8_SA(b, h) + aoff + m * 2048 + k * 1024); } while (0)
; #define PG8_LDB(dst, b, h) do { _Pragma("unroll") for (int n = 0; n < 2; ++n) _Pragma("unroll") for (int k = 0; k < 2; ++k) dst[n][k] = *(const PG8_LAS bf16x8*)(lds + PG8_SB(b, h) + boff + n * 2048 + k * 1024); } while (0)
; #define PG8_MMA(ai, bj, At, Bt) do { __builtin_amdgcn_s_setprio(1); _Pragma("unroll") for (int m = 0; m < 4; ++m) _Pragma("unroll") for (int n = 0; n < 2; ++n) _Pragma("unroll") for (int k = 0; k < 2; ++k) \
;         acc[ai][bj][m][n] = __builtin_amdgcn_mfma_f32_16x16x32_bf16(Bt[n][k], At[m][k], acc[ai][bj][m][n], 0, 0, 0); __builtin_amdgcn_s_setprio(0); } while (0)
; #define PG8_WAIT_V(n) asm volatile("s_waitcnt vmcnt(" #n ")" ::: "memory")
; #define PG8_WAIT_L(n) asm volatile("s_waitcnt lgkmcnt(" #n ")" ::: "memory")
; #define PG8_BAR __builtin_amdgcn_s_barrier()
; #define PG8_SCHED __builtin_amdgcn_sched_barrier(0)
; template <class Epi, class Sched, bool ALIGN_EPI = false, bool SP2 = false>
; __device__ __forceinline__ void gemm_phase(PG8_LAS unsigned char* lds, const Gemm g, const Sched& S, const Epi& E) {
;     ...
;             PG8_WAIT_V(8); PG8_WAIT_L(0); PG8_BAR; PG8_MMA(1, 0, At, B0); PG8_MMA(1, 1, At, B1); PG8_BAR; PG8_SCHED;
;             PG8_LDB(B0, 1, 0); PG8_LDB(B1, 1, 1); PG8_SCHED; PG8_LDA(At, 1, 0); PG8_STAGE(PG8_SA(0, 1), a2 + hstep, voffA);
;             PG8_WAIT_V(8); PG8_WAIT_L(0); PG8_BAR; PG8_MMA(0, 0, At, B0); PG8_MMA(0, 1, At, B1); PG8_BAR; PG8_SCHED;
	v_mfma_f32_16x16x32_bf16 v[62:65], v[152:155], v[188:191], v[62:65]
	v_mfma_f32_16x16x32_bf16 v[58:61], v[164:167], v[188:191], v[58:61]
	v_mfma_f32_16x16x32_bf16 v[50:53], v[152:155], v[196:199], v[50:53]
	v_mfma_f32_16x16x32_bf16 v[42:45], v[164:167], v[196:199], v[42:45]
	v_mfma_f32_16x16x32_bf16 v[34:37], v[152:155], v[220:223], v[34:37]
	v_mfma_f32_16x16x32_bf16 v[26:29], v[164:167], v[220:223], v[26:29]
	v_mfma_f32_16x16x32_bf16 v[18:21], v[152:155], v[228:231], v[18:21]
	v_mfma_f32_16x16x32_bf16 v[10:13], v[164:167], v[228:231], v[10:13]
	v_mfma_f32_16x16x32_bf16 v[62:65], v[160:163], v[192:195], v[62:65]
	v_mfma_f32_16x16x32_bf16 v[58:61], v[168:171], v[192:195], v[58:61]
	v_mfma_f32_16x16x32_bf16 v[50:53], v[160:163], v[216:219], v[50:53]
	v_mfma_f32_16x16x32_bf16 v[42:45], v[168:171], v[216:219], v[42:45]
	v_mfma_f32_16x16x32_bf16 v[34:37], v[160:163], v[224:227], v[34:37]
	v_mfma_f32_16x16x32_bf16 v[26:29], v[168:171], v[224:227], v[26:29]
	v_mfma_f32_16x16x32_bf16 v[18:21], v[160:163], v[232:235], v[18:21]
	v_mfma_f32_16x16x32_bf16 v[10:13], v[168:171], v[232:235], v[10:13]
	v_mfma_f32_16x16x32_bf16 v[54:57], v[172:175], v[188:191], v[54:57]
	v_mfma_f32_16x16x32_bf16 v[46:49], v[180:183], v[188:191], v[46:49]
	v_mfma_f32_16x16x32_bf16 v[38:41], v[172:175], v[196:199], v[38:41]
	v_mfma_f32_16x16x32_bf16 v[30:33], v[180:183], v[196:199], v[30:33]
	v_mfma_f32_16x16x32_bf16 v[22:25], v[172:175], v[220:223], v[22:25]
	v_mfma_f32_16x16x32_bf16 v[14:17], v[180:183], v[220:223], v[14:17]
	v_mfma_f32_16x16x32_bf16 v[6:9], v[172:175], v[228:231], v[6:9]
	v_mfma_f32_16x16x32_bf16 v[2:5], v[180:183], v[228:231], v[2:5]
	v_mfma_f32_16x16x32_bf16 v[54:57], v[176:179], v[192:195], v[54:57]
	v_mfma_f32_16x16x32_bf16 v[46:49], v[184:187], v[192:195], v[46:49]
	v_mfma_f32_16x16x32_bf16 v[38:41], v[176:179], v[216:219], v[38:41]
	v_mfma_f32_16x16x32_bf16 v[30:33], v[184:187], v[216:219], v[30:33]
	v_mfma_f32_16x16x32_bf16 v[22:25], v[176:179], v[224:227], v[22:25]
	v_mfma_f32_16x16x32_bf16 v[14:17], v[184:187], v[224:227], v[14:17]
	v_mfma_f32_16x16x32_bf16 v[6:9], v[176:179], v[232:235], v[6:9]
	v_mfma_f32_16x16x32_bf16 v[2:5], v[184:187], v[232:235], v[2:5]
	s_barrier
	s_setprio 1
	s_add_i32 s10, 0, 0x18000
	s_add_i32 s11, 0, 0x1c000
	v_add_u32_e32 v168, s10, v157
	v_add_u32_e32 v184, s11, v157
	ds_read_b128 v[152:155], v168
	ds_read_b128 v[160:163], v168 offset:1024
	ds_read_b128 v[164:167], v168 offset:2048
	ds_read_b128 v[168:171], v168 offset:3072
	ds_read_b128 v[172:175], v184
	ds_read_b128 v[176:179], v184 offset:1024
	ds_read_b128 v[180:183], v184 offset:2048
	ds_read_b128 v[184:187], v184 offset:3072
	s_add_u32 s38, s50, 0x80000
	s_addc_u32 s39, s51, 0
	s_mov_b32 m0, s59
	v_lshl_add_u64 v[242:243], s[38:39], 0, v[146:147]
	ds_read_b128 v[188:191], v159 offset:32768
	ds_read_b128 v[192:195], v159 offset:33792
	ds_read_b128 v[196:199], v159 offset:34816
	ds_read_b128 v[216:219], v159 offset:35840
	ds_read_b128 v[220:223], v159 offset:36864
	ds_read_b128 v[224:227], v159 offset:37888
	ds_read_b128 v[228:231], v159 offset:38912
	ds_read_b128 v[232:235], v159 offset:39936
	global_load_lds_dwordx4 v[242:243], off
	v_lshl_add_u64 v[242:243], s[38:39], 0, v[144:145]
	s_mov_b32 m0, s60
	s_nop 0
	global_load_lds_dwordx4 v[242:243], off
	s_waitcnt vmcnt(8)
	s_waitcnt lgkmcnt(0)
	s_setprio 0
	s_barrier
	v_mfma_f32_16x16x32_bf16 v[126:129], v[152:155], v[188:191], v[126:129]
	v_mfma_f32_16x16x32_bf16 v[122:125], v[164:167], v[188:191], v[122:125]
	v_mfma_f32_16x16x32_bf16 v[110:113], v[152:155], v[196:199], v[110:113]
	v_mfma_f32_16x16x32_bf16 v[106:109], v[164:167], v[196:199], v[106:109]
	v_mfma_f32_16x16x32_bf16 v[94:97], v[152:155], v[220:223], v[94:97]
	v_mfma_f32_16x16x32_bf16 v[90:93], v[164:167], v[220:223], v[90:93]
	v_mfma_f32_16x16x32_bf16 v[78:81], v[152:155], v[228:231], v[78:81]
	v_mfma_f32_16x16x32_bf16 v[74:77], v[164:167], v[228:231], v[74:77]
	v_mfma_f32_16x16x32_bf16 v[126:129], v[160:163], v[192:195], v[126:129]
	v_mfma_f32_16x16x32_bf16 v[122:125], v[168:171], v[192:195], v[122:125]
	v_mfma_f32_16x16x32_bf16 v[110:113], v[160:163], v[216:219], v[110:113]
	v_mfma_f32_16x16x32_bf16 v[106:109], v[168:171], v[216:219], v[106:109]
	v_mfma_f32_16x16x32_bf16 v[94:97], v[160:163], v[224:227], v[94:97]
	v_mfma_f32_16x16x32_bf16 v[90:93], v[168:171], v[224:227], v[90:93]
	v_mfma_f32_16x16x32_bf16 v[78:81], v[160:163], v[232:235], v[78:81]
	v_mfma_f32_16x16x32_bf16 v[74:77], v[168:171], v[232:235], v[74:77]
	v_mfma_f32_16x16x32_bf16 v[118:121], v[172:175], v[188:191], v[118:121]
	v_mfma_f32_16x16x32_bf16 v[114:117], v[180:183], v[188:191], v[114:117]
	v_mfma_f32_16x16x32_bf16 v[102:105], v[172:175], v[196:199], v[102:105]
	v_mfma_f32_16x16x32_bf16 v[98:101], v[180:183], v[196:199], v[98:101]
	v_mfma_f32_16x16x32_bf16 v[86:89], v[172:175], v[220:223], v[86:89]
	v_mfma_f32_16x16x32_bf16 v[82:85], v[180:183], v[220:223], v[82:85]
	v_mfma_f32_16x16x32_bf16 v[70:73], v[172:175], v[228:231], v[70:73]
	v_mfma_f32_16x16x32_bf16 v[66:69], v[180:183], v[228:231], v[66:69]
	v_mfma_f32_16x16x32_bf16 v[118:121], v[176:179], v[192:195], v[118:121]
	v_mfma_f32_16x16x32_bf16 v[114:117], v[184:187], v[192:195], v[114:117]
	v_mfma_f32_16x16x32_bf16 v[102:105], v[176:179], v[216:219], v[102:105]
	v_mfma_f32_16x16x32_bf16 v[98:101], v[184:187], v[216:219], v[98:101]
	v_mfma_f32_16x16x32_bf16 v[86:89], v[176:179], v[224:227], v[86:89]
	v_mfma_f32_16x16x32_bf16 v[82:85], v[184:187], v[224:227], v[82:85]
	v_mfma_f32_16x16x32_bf16 v[70:73], v[176:179], v[232:235], v[70:73]
	v_mfma_f32_16x16x32_bf16 v[66:69], v[184:187], v[232:235], v[66:69]
	s_barrier
; #define PG8_STAGE(bufoff, gbase, voff) do { _Pragma("unroll") for (int _i = 0; _i < 2; ++_i) \
;         __builtin_amdgcn_global_load_lds((const unsigned*)((const char*)(gbase) + (voff)[_i]), (PG8_LAS unsigned*)(lds + (bufoff) + ldsw + _i * 8192), 16, 0, 0); } while (0)
; #define PG8_LDA(dst, b, h) do { _Pragma("unroll") for (int m = 0; m < 4; ++m) _Pragma("unroll") for (int k = 0; k < 2; ++k) dst[m][k] = *(const PG8_LAS bf16x8*)(lds + PG8_SA(b, h) + aoff + m * 2048 + k * 1024); } while (0)
; #define PG8_MMA(ai, bj, At, Bt) do { __builtin_amdgcn_s_setprio(1); _Pragma("unroll") for (int m = 0; m < 4; ++m) _Pragma("unroll") for (int n = 0; n < 2; ++n) _Pragma("unroll") for (int k = 0; k < 2; ++k) \
;         acc[ai][bj][m][n] = __builtin_amdgcn_mfma_f32_16x16x32_bf16(Bt[n][k], At[m][k], acc[ai][bj][m][n], 0, 0, 0); __builtin_amdgcn_s_setprio(0); } while (0)
; #define PG8_WAIT_V(n) asm volatile("s_waitcnt vmcnt(" #n ")" ::: "memory")
; #define PG8_WAIT_L(n) asm volatile("s_waitcnt lgkmcnt(" #n ")" ::: "memory")
; #define PG8_BAR __builtin_amdgcn_s_barrier()
; #define PG8_SCHED __builtin_amdgcn_sched_barrier(0)
; template <class Epi, class Sched, bool ALIGN_EPI = false, bool SP2 = false>
; __device__ __forceinline__ void gemm_phase(PG8_LAS unsigned char* lds, const Gemm g, const Sched& S, const Epi& E) {
;     ...
;             PG8_LDA(At, 1, 1); PG8_STAGE(PG8_SB(1, 0), b3, voffB); PG8_STAGE(PG8_SB(1, 1), b3 + hstep, voffB); PG8_STAGE(PG8_SA(1, 0), a3, voffA);
;             PG8_WAIT_V(8); PG8_WAIT_L(0); PG8_BAR; PG8_MMA(1, 0, At, B0); PG8_MMA(1, 1, At, B1); PG8_BAR; PG8_SCHED;
;     ...
;         if constexpr (ALIGN_EPI) { if (wr == 0) PG8_BAR; }
	s_setprio 1
	s_add_i32 s10, s10, s56
	v_lshl_add_u64 v[200:201], v[200:201], 0, s[30:31]
	s_mov_b32 m0, s10
	ds_read_b128 v[188:191], v159 offset:49152
	ds_read_b128 v[192:195], v159 offset:50176
	ds_read_b128 v[196:199], v159 offset:51200
	ds_read_b128 v[216:219], v159 offset:52224
	ds_read_b128 v[220:223], v159 offset:53248
	ds_read_b128 v[224:227], v159 offset:54272
	ds_read_b128 v[228:231], v159 offset:55296
	ds_read_b128 v[232:235], v159 offset:56320
	global_load_lds_dwordx4 v[200:201], off
	s_add_i32 m0, s10, 0x2000
	s_add_u32 s18, s18, 0x80080
	v_lshl_add_u64 v[200:201], v[236:237], 0, s[30:31]
	s_addc_u32 s19, s19, 0
	s_add_i32 s10, s11, s56
	global_load_lds_dwordx4 v[200:201], off
	v_lshl_add_u64 v[200:201], s[18:19], 0, v[0:1]
	s_mov_b32 m0, s10
	s_nop 0
	global_load_lds_dwordx4 v[200:201], off
	v_lshl_add_u64 v[200:201], s[18:19], 0, v[142:143]
	s_add_i32 m0, s10, 0x2000
	s_nop 0
	global_load_lds_dwordx4 v[200:201], off
	v_lshl_add_u64 v[200:201], v[238:239], 0, s[30:31]
	s_mov_b32 m0, s61
	s_nop 0
	global_load_lds_dwordx4 v[200:201], off
	v_lshl_add_u64 v[200:201], v[240:241], 0, s[30:31]
	s_mov_b32 m0, s62
	s_nop 0
	global_load_lds_dwordx4 v[200:201], off
	s_waitcnt vmcnt(8)
	s_waitcnt lgkmcnt(0)
	s_setprio 0
	s_barrier
	v_mfma_f32_16x16x32_bf16 v[62:65], v[152:155], v[188:191], v[62:65]
	v_mfma_f32_16x16x32_bf16 v[58:61], v[164:167], v[188:191], v[58:61]
	v_mfma_f32_16x16x32_bf16 v[50:53], v[152:155], v[196:199], v[50:53]
	v_mfma_f32_16x16x32_bf16 v[42:45], v[164:167], v[196:199], v[42:45]
	v_mfma_f32_16x16x32_bf16 v[34:37], v[152:155], v[220:223], v[34:37]
	v_mfma_f32_16x16x32_bf16 v[26:29], v[164:167], v[220:223], v[26:29]
	v_mfma_f32_16x16x32_bf16 v[18:21], v[152:155], v[228:231], v[18:21]
	v_mfma_f32_16x16x32_bf16 v[10:13], v[164:167], v[228:231], v[10:13]
	v_mfma_f32_16x16x32_bf16 v[62:65], v[160:163], v[192:195], v[62:65]
	v_mfma_f32_16x16x32_bf16 v[58:61], v[168:171], v[192:195], v[58:61]
	v_mfma_f32_16x16x32_bf16 v[50:53], v[160:163], v[216:219], v[50:53]
	v_mfma_f32_16x16x32_bf16 v[42:45], v[168:171], v[216:219], v[42:45]
	v_mfma_f32_16x16x32_bf16 v[34:37], v[160:163], v[224:227], v[34:37]
	v_mfma_f32_16x16x32_bf16 v[26:29], v[168:171], v[224:227], v[26:29]
	v_mfma_f32_16x16x32_bf16 v[18:21], v[160:163], v[232:235], v[18:21]
	v_mfma_f32_16x16x32_bf16 v[10:13], v[168:171], v[232:235], v[10:13]
	v_mfma_f32_16x16x32_bf16 v[54:57], v[172:175], v[188:191], v[54:57]
	v_mfma_f32_16x16x32_bf16 v[46:49], v[180:183], v[188:191], v[46:49]
	v_mfma_f32_16x16x32_bf16 v[38:41], v[172:175], v[196:199], v[38:41]
	v_mfma_f32_16x16x32_bf16 v[30:33], v[180:183], v[196:199], v[30:33]
	v_mfma_f32_16x16x32_bf16 v[22:25], v[172:175], v[220:223], v[22:25]
	v_mfma_f32_16x16x32_bf16 v[14:17], v[180:183], v[220:223], v[14:17]
	v_mfma_f32_16x16x32_bf16 v[6:9], v[172:175], v[228:231], v[6:9]
	v_mfma_f32_16x16x32_bf16 v[2:5], v[180:183], v[228:231], v[2:5]
	v_mfma_f32_16x16x32_bf16 v[54:57], v[176:179], v[192:195], v[54:57]
	v_mfma_f32_16x16x32_bf16 v[46:49], v[184:187], v[192:195], v[46:49]
	v_mfma_f32_16x16x32_bf16 v[38:41], v[176:179], v[216:219], v[38:41]
	v_mfma_f32_16x16x32_bf16 v[30:33], v[184:187], v[216:219], v[30:33]
	v_mfma_f32_16x16x32_bf16 v[22:25], v[176:179], v[224:227], v[22:25]
	v_mfma_f32_16x16x32_bf16 v[14:17], v[184:187], v[224:227], v[14:17]
	v_mfma_f32_16x16x32_bf16 v[6:9], v[176:179], v[232:235], v[6:9]
	v_mfma_f32_16x16x32_bf16 v[2:5], v[184:187], v[232:235], v[2:5]
	s_barrier
	s_setprio 1
	s_add_i32 s23, s23, 2
	s_add_u32 s16, s16, 0x100
	s_addc_u32 s17, s17, 0
	s_add_u32 s15, s15, 0x100
	s_addc_u32 s22, s22, 0
	s_cmp_gt_u32 s23, 29
	s_cbranch_scc0 .LBB0_265
	s_and_b64 vcc, exec, s[24:25]
	s_cbranch_vccz .LBB0_268
	s_barrier

; #define PG8_STAGE(bufoff, gbase, voff) do { _Pragma("unroll") for (int _i = 0; _i < 2; ++_i) \
;         __builtin_amdgcn_global_load_lds((const unsigned*)((const char*)(gbase) + (voff)[_i]), (PG8_LAS unsigned*)(lds + (bufoff) + ldsw + _i * 8192), 16, 0, 0); } while (0)
; #define PG8_LDA(dst, b, h) do { _Pragma("unroll") for (int m = 0; m < 4; ++m) _Pragma("unroll") for (int k = 0; k < 2; ++k) dst[m][k] = *(const PG8_LAS bf16x8*)(lds + PG8_SA(b, h) + aoff + m * 2048 + k * 1024); } while (0)
; #define PG8_LDB(dst, b, h) do { _Pragma("unroll") for (int n = 0; n < 2; ++n) _Pragma("unroll") for (int k = 0; k < 2; ++k) dst[n][k] = *(const PG8_LAS bf16x8*)(lds + PG8_SB(b, h) + boff + n * 2048 + k * 1024); } while (0)
; #define PG8_MMA(ai, bj, At, Bt) do { __builtin_amdgcn_s_setprio(1); _Pragma("unroll") for (int m = 0; m < 4; ++m) _Pragma("unroll") for (int n = 0; n < 2; ++n) _Pragma("unroll") for (int k = 0; k < 2; ++k) \
;         acc[ai][bj][m][n] = __builtin_amdgcn_mfma_f32_16x16x32_bf16(Bt[n][k], At[m][k], acc[ai][bj][m][n], 0, 0, 0); __builtin_amdgcn_s_setprio(0); } while (0)
; #define PG8_WAIT_V(n) asm volatile("s_waitcnt vmcnt(" #n ")" ::: "memory")
; #define PG8_WAIT_L(n) asm volatile("s_waitcnt lgkmcnt(" #n ")" ::: "memory")
; template <class Epi, class Sched, bool ALIGN_EPI = false, bool SP2 = false>
; __device__ __forceinline__ void gemm_phase(PG8_LAS unsigned char* lds, const Gemm g, const Sched& S, const Epi& E) {
;     ...
;             const bool last = (t == nt - 2);
;             const char* a1 = cA + (size_t)(t + 1) * kstep;
;             const char* a2 = last ? nA : cA + (size_t)(t + 2) * kstep; const char* b2 = last ? nB : cB + (size_t)(t + 2) * kstep;
;             const char* a3 = a2 + kstep; const char* b3 = b2 + kstep;
;             if (last && has_next) S.a_ready(nxt);
;             if constexpr (SP2) {
;             PG8_LDB(B0, 0, 0); PG8_LDB(B1, 0, 1); PG8_SCHED; PG8_LDA(At, 0, 0); PG8_STAGE(PG8_SA(1, 1), a1 + hstep, voffA);
;             PG8_WAIT_V(8); PG8_WAIT_L(0); PG8_BAR; PG8_MMA(0, 0, At, B0); PG8_MMA(0, 1, At, B1); PG8_BAR; PG8_SCHED;
;             PG8_LDA(At, 0, 1); PG8_STAGE(PG8_SB(0, 0), b2, voffB); PG8_STAGE(PG8_SB(0, 1), b2 + hstep, voffB); PG8_STAGE(PG8_SA(0, 0), a2, voffA);
;             PG8_WAIT_V(8); PG8_WAIT_L(0); PG8_BAR; PG8_MMA(1, 0, At, B0); PG8_MMA(1, 1, At, B1); PG8_BAR; PG8_SCHED;
.LBB0_601:
	s_add_u32 s18, s16, 0x100
	s_addc_u32 s19, s17, 0
	s_add_i32 s10, 0, 0x10000
	s_cmp_eq_u32 s22, 28
	s_cselect_b32 s27, s5, s19
	s_cselect_b32 s26, s7, s18
	s_cselect_b32 s25, s8, s15
	s_cselect_b32 s24, s9, s14
	s_add_i32 s12, 0, 0x14000
	v_add_u32_e32 v160, s10, v187
	v_add_u32_e32 v176, s12, v187
	ds_read_b128 v[148:151], v160
	ds_read_b128 v[152:155], v160 offset:1024
	ds_read_b128 v[156:159], v160 offset:2048
	ds_read_b128 v[160:163], v160 offset:3072
	ds_read_b128 v[164:167], v176
	ds_read_b128 v[168:171], v176 offset:1024
	ds_read_b128 v[172:175], v176 offset:2048
	ds_read_b128 v[176:179], v176 offset:3072
	v_lshl_add_u64 v[184:185], s[16:17], 0, v[144:145]
	s_add_i32 m0, s61, 0xc000
	ds_read_b128 v[180:183], v189
	ds_read_b128 v[190:193], v189 offset:1024
	ds_read_b128 v[194:197], v189 offset:2048
	ds_read_b128 v[198:201], v189 offset:3072
	ds_read_b128 v[216:219], v189 offset:4096
	ds_read_b128 v[220:223], v189 offset:5120
	ds_read_b128 v[224:227], v189 offset:6144
	ds_read_b128 v[228:231], v189 offset:7168
	global_load_lds_dwordx4 v[184:185], off
	v_lshl_add_u64 v[184:185], s[16:17], 0, v[146:147]
	s_add_i32 m0, s61, 0xe000
	s_nop 0
	global_load_lds_dwordx4 v[184:185], off
	s_waitcnt vmcnt(8)
	s_waitcnt lgkmcnt(0)
	s_setprio 0
	s_barrier
	v_mfma_f32_16x16x32_bf16 v[126:129], v[148:151], v[180:183], v[126:129]
	v_mfma_f32_16x16x32_bf16 v[122:125], v[156:159], v[180:183], v[122:125]
	v_mfma_f32_16x16x32_bf16 v[110:113], v[148:151], v[194:197], v[110:113]
	v_mfma_f32_16x16x32_bf16 v[106:109], v[156:159], v[194:197], v[106:109]
	v_mfma_f32_16x16x32_bf16 v[94:97], v[148:151], v[216:219], v[94:97]
	v_mfma_f32_16x16x32_bf16 v[90:93], v[156:159], v[216:219], v[90:93]
	v_mfma_f32_16x16x32_bf16 v[78:81], v[148:151], v[224:227], v[78:81]
	v_mfma_f32_16x16x32_bf16 v[74:77], v[156:159], v[224:227], v[74:77]
	v_mfma_f32_16x16x32_bf16 v[126:129], v[152:155], v[190:193], v[126:129]
	v_mfma_f32_16x16x32_bf16 v[122:125], v[160:163], v[190:193], v[122:125]
	v_mfma_f32_16x16x32_bf16 v[110:113], v[152:155], v[198:201], v[110:113]
	v_mfma_f32_16x16x32_bf16 v[106:109], v[160:163], v[198:201], v[106:109]
	v_mfma_f32_16x16x32_bf16 v[94:97], v[152:155], v[220:223], v[94:97]
	v_mfma_f32_16x16x32_bf16 v[90:93], v[160:163], v[220:223], v[90:93]
	v_mfma_f32_16x16x32_bf16 v[78:81], v[152:155], v[228:231], v[78:81]
	v_mfma_f32_16x16x32_bf16 v[74:77], v[160:163], v[228:231], v[74:77]
	v_mfma_f32_16x16x32_bf16 v[118:121], v[164:167], v[180:183], v[118:121]
	v_mfma_f32_16x16x32_bf16 v[114:117], v[172:175], v[180:183], v[114:117]
	v_mfma_f32_16x16x32_bf16 v[102:105], v[164:167], v[194:197], v[102:105]
	v_mfma_f32_16x16x32_bf16 v[98:101], v[172:175], v[194:197], v[98:101]
	v_mfma_f32_16x16x32_bf16 v[86:89], v[164:167], v[216:219], v[86:89]
	v_mfma_f32_16x16x32_bf16 v[82:85], v[172:175], v[216:219], v[82:85]
	v_mfma_f32_16x16x32_bf16 v[70:73], v[164:167], v[224:227], v[70:73]
	v_mfma_f32_16x16x32_bf16 v[66:69], v[172:175], v[224:227], v[66:69]
	v_mfma_f32_16x16x32_bf16 v[118:121], v[168:171], v[190:193], v[118:121]
	v_mfma_f32_16x16x32_bf16 v[114:117], v[176:179], v[190:193], v[114:117]
	v_mfma_f32_16x16x32_bf16 v[102:105], v[168:171], v[198:201], v[102:105]
	v_mfma_f32_16x16x32_bf16 v[98:101], v[176:179], v[198:201], v[98:101]
	v_mfma_f32_16x16x32_bf16 v[86:89], v[168:171], v[220:223], v[86:89]
	v_mfma_f32_16x16x32_bf16 v[82:85], v[176:179], v[220:223], v[82:85]
	v_mfma_f32_16x16x32_bf16 v[70:73], v[168:171], v[228:231], v[70:73]
	v_mfma_f32_16x16x32_bf16 v[66:69], v[176:179], v[228:231], v[66:69]
	s_barrier
	s_setprio 1
	s_add_i32 s10, s10, s60
	v_lshl_add_u64 v[184:185], s[24:25], 0, v[0:1]
	s_mov_b32 m0, s10
	ds_read_b128 v[180:183], v189 offset:16384
	ds_read_b128 v[190:193], v189 offset:17408
	ds_read_b128 v[194:197], v189 offset:18432
	ds_read_b128 v[198:201], v189 offset:19456
	ds_read_b128 v[216:219], v189 offset:20480
	ds_read_b128 v[220:223], v189 offset:21504
	ds_read_b128 v[224:227], v189 offset:22528
	ds_read_b128 v[228:231], v189 offset:23552
	global_load_lds_dwordx4 v[184:185], off
	s_add_i32 m0, s10, 0x2000
	s_add_u32 s10, s24, 0x80000
	v_lshl_add_u64 v[232:233], s[24:25], 0, v[142:143]
	s_addc_u32 s11, s25, 0
	s_add_i32 s12, s12, s60
	global_load_lds_dwordx4 v[232:233], off
	v_lshl_add_u64 v[234:235], s[10:11], 0, v[0:1]
	s_mov_b32 m0, s12
	v_lshl_add_u64 v[236:237], s[26:27], 0, v[142:143]
	global_load_lds_dwordx4 v[234:235], off
	v_lshl_add_u64 v[234:235], s[10:11], 0, v[142:143]
	s_add_i32 m0, s12, 0x2000
	s_nop 0
	global_load_lds_dwordx4 v[234:235], off
	v_lshl_add_u64 v[234:235], s[26:27], 0, v[0:1]
	s_mov_b32 m0, s61
	s_nop 0
	global_load_lds_dwordx4 v[234:235], off
	s_mov_b32 m0, s62
	s_nop 0
	global_load_lds_dwordx4 v[236:237], off
	s_waitcnt vmcnt(8)
	s_waitcnt lgkmcnt(0)
	s_setprio 0
	s_barrier
; #define PG8_STAGE(bufoff, gbase, voff) do { _Pragma("unroll") for (int _i = 0; _i < 2; ++_i) \
;         __builtin_amdgcn_global_load_lds((const unsigned*)((const char*)(gbase) + (voff)[_i]), (PG8_LAS unsigned*)(lds + (bufoff) + ldsw + _i * 8192), 16, 0, 0); } while (0)
; #define PG8_LDA(dst, b, h) do { _Pragma("unroll") for (int m = 0; m < 4; ++m) _Pragma("unroll") for (int k = 0; k < 2; ++k) dst[m][k] = *(const PG8_LAS bf16x8*)(lds + PG8_SA(b, h) + aoff + m * 2048 + k * 1024); } while (0)
; #define PG8_LDB(dst, b, h) do { _Pragma("unroll") for (int n = 0; n < 2; ++n) _Pragma("unroll") for (int k = 0; k < 2; ++k) dst[n][k] = *(const PG8_LAS bf16x8*)(lds + PG8_SB(b, h) + boff + n * 2048 + k * 1024); } while (0)
; #define PG8_MMA(ai, bj, At, Bt) do { __builtin_amdgcn_s_setprio(1); _Pragma("unroll") for (int m = 0; m < 4; ++m) _Pragma("unroll") for (int n = 0; n < 2; ++n) _Pragma("unroll") for (int k = 0; k < 2; ++k) \
;         acc[ai][bj][m][n] = __builtin_amdgcn_mfma_f32_16x16x32_bf16(Bt[n][k], At[m][k], acc[ai][bj][m][n], 0, 0, 0); __builtin_amdgcn_s_setprio(0); } while (0)
; #define PG8_WAIT_V(n) asm volatile("s_waitcnt vmcnt(" #n ")" ::: "memory")
; #define PG8_WAIT_L(n) asm volatile("s_waitcnt lgkmcnt(" #n ")" ::: "memory")
; #define PG8_BAR __builtin_amdgcn_s_barrier()
; #define PG8_SCHED __builtin_amdgcn_sched_barrier(0)
; template <class Epi, class Sched, bool ALIGN_EPI = false, bool SP2 = false>
; __device__ __forceinline__ void gemm_phase(PG8_LAS unsigned char* lds, const Gemm g, const Sched& S, const Epi& E) {
;     ...
;             PG8_WAIT_V(8); PG8_WAIT_L(0); PG8_BAR; PG8_MMA(1, 0, At, B0); PG8_MMA(1, 1, At, B1); PG8_BAR; PG8_SCHED;
;             PG8_LDB(B0, 1, 0); PG8_LDB(B1, 1, 1); PG8_SCHED; PG8_LDA(At, 1, 0); PG8_STAGE(PG8_SA(0, 1), a2 + hstep, voffA);
;             PG8_WAIT_V(8); PG8_WAIT_L(0); PG8_BAR; PG8_MMA(0, 0, At, B0); PG8_MMA(0, 1, At, B1); PG8_BAR; PG8_SCHED;
	v_mfma_f32_16x16x32_bf16 v[62:65], v[148:151], v[180:183], v[62:65]
	v_mfma_f32_16x16x32_bf16 v[58:61], v[156:159], v[180:183], v[58:61]
	v_mfma_f32_16x16x32_bf16 v[46:49], v[148:151], v[194:197], v[46:49]
	v_mfma_f32_16x16x32_bf16 v[42:45], v[156:159], v[194:197], v[42:45]
	v_mfma_f32_16x16x32_bf16 v[30:33], v[148:151], v[216:219], v[30:33]
	v_mfma_f32_16x16x32_bf16 v[26:29], v[156:159], v[216:219], v[26:29]
	v_mfma_f32_16x16x32_bf16 v[14:17], v[148:151], v[224:227], v[14:17]
	v_mfma_f32_16x16x32_bf16 v[10:13], v[156:159], v[224:227], v[10:13]
	v_mfma_f32_16x16x32_bf16 v[62:65], v[152:155], v[190:193], v[62:65]
	v_mfma_f32_16x16x32_bf16 v[58:61], v[160:163], v[190:193], v[58:61]
	v_mfma_f32_16x16x32_bf16 v[46:49], v[152:155], v[198:201], v[46:49]
	v_mfma_f32_16x16x32_bf16 v[42:45], v[160:163], v[198:201], v[42:45]
	v_mfma_f32_16x16x32_bf16 v[30:33], v[152:155], v[220:223], v[30:33]
	v_mfma_f32_16x16x32_bf16 v[26:29], v[160:163], v[220:223], v[26:29]
	v_mfma_f32_16x16x32_bf16 v[14:17], v[152:155], v[228:231], v[14:17]
	v_mfma_f32_16x16x32_bf16 v[10:13], v[160:163], v[228:231], v[10:13]
	v_mfma_f32_16x16x32_bf16 v[54:57], v[164:167], v[180:183], v[54:57]
	v_mfma_f32_16x16x32_bf16 v[50:53], v[172:175], v[180:183], v[50:53]
	v_mfma_f32_16x16x32_bf16 v[38:41], v[164:167], v[194:197], v[38:41]
	v_mfma_f32_16x16x32_bf16 v[34:37], v[172:175], v[194:197], v[34:37]
	v_mfma_f32_16x16x32_bf16 v[22:25], v[164:167], v[216:219], v[22:25]
	v_mfma_f32_16x16x32_bf16 v[18:21], v[172:175], v[216:219], v[18:21]
	v_mfma_f32_16x16x32_bf16 v[6:9], v[164:167], v[224:227], v[6:9]
	v_mfma_f32_16x16x32_bf16 v[2:5], v[172:175], v[224:227], v[2:5]
	v_mfma_f32_16x16x32_bf16 v[54:57], v[168:171], v[190:193], v[54:57]
	v_mfma_f32_16x16x32_bf16 v[50:53], v[176:179], v[190:193], v[50:53]
	v_mfma_f32_16x16x32_bf16 v[38:41], v[168:171], v[198:201], v[38:41]
	v_mfma_f32_16x16x32_bf16 v[34:37], v[176:179], v[198:201], v[34:37]
	v_mfma_f32_16x16x32_bf16 v[22:25], v[168:171], v[220:223], v[22:25]
	v_mfma_f32_16x16x32_bf16 v[18:21], v[176:179], v[220:223], v[18:21]
	v_mfma_f32_16x16x32_bf16 v[6:9], v[168:171], v[228:231], v[6:9]
	v_mfma_f32_16x16x32_bf16 v[2:5], v[176:179], v[228:231], v[2:5]
	s_barrier
	s_setprio 1
	s_add_i32 s12, 0, 0x18000
	s_add_i32 s13, 0, 0x1c000
	v_add_u32_e32 v160, s12, v187
	v_add_u32_e32 v176, s13, v187
	ds_read_b128 v[148:151], v160
	ds_read_b128 v[152:155], v160 offset:1024
	ds_read_b128 v[156:159], v160 offset:2048
	ds_read_b128 v[160:163], v160 offset:3072
	ds_read_b128 v[164:167], v176
	ds_read_b128 v[168:171], v176 offset:1024
	ds_read_b128 v[172:175], v176 offset:2048
	ds_read_b128 v[176:179], v176 offset:3072
	s_add_u32 s10, s26, 0x80000
	s_addc_u32 s11, s27, 0
	s_mov_b32 m0, s63
	v_lshl_add_u64 v[238:239], s[10:11], 0, v[0:1]
	ds_read_b128 v[180:183], v189 offset:32768
	ds_read_b128 v[190:193], v189 offset:33792
	ds_read_b128 v[194:197], v189 offset:34816
	ds_read_b128 v[198:201], v189 offset:35840
	ds_read_b128 v[216:219], v189 offset:36864
	ds_read_b128 v[220:223], v189 offset:37888
	ds_read_b128 v[224:227], v189 offset:38912
	ds_read_b128 v[228:231], v189 offset:39936
	global_load_lds_dwordx4 v[238:239], off
	v_lshl_add_u64 v[238:239], s[10:11], 0, v[142:143]
	s_mov_b32 m0, s64
	s_nop 0
	global_load_lds_dwordx4 v[238:239], off
	s_waitcnt vmcnt(8)
	s_waitcnt lgkmcnt(0)
	s_setprio 0
	s_barrier
	v_mfma_f32_16x16x32_bf16 v[126:129], v[148:151], v[180:183], v[126:129]
	v_mfma_f32_16x16x32_bf16 v[122:125], v[156:159], v[180:183], v[122:125]
	v_mfma_f32_16x16x32_bf16 v[110:113], v[148:151], v[194:197], v[110:113]
	v_mfma_f32_16x16x32_bf16 v[106:109], v[156:159], v[194:197], v[106:109]
	v_mfma_f32_16x16x32_bf16 v[94:97], v[148:151], v[216:219], v[94:97]
	v_mfma_f32_16x16x32_bf16 v[90:93], v[156:159], v[216:219], v[90:93]
	v_mfma_f32_16x16x32_bf16 v[78:81], v[148:151], v[224:227], v[78:81]
	v_mfma_f32_16x16x32_bf16 v[74:77], v[156:159], v[224:227], v[74:77]
	v_mfma_f32_16x16x32_bf16 v[126:129], v[152:155], v[190:193], v[126:129]
	v_mfma_f32_16x16x32_bf16 v[122:125], v[160:163], v[190:193], v[122:125]
	v_mfma_f32_16x16x32_bf16 v[110:113], v[152:155], v[198:201], v[110:113]
	v_mfma_f32_16x16x32_bf16 v[106:109], v[160:163], v[198:201], v[106:109]
	v_mfma_f32_16x16x32_bf16 v[94:97], v[152:155], v[220:223], v[94:97]
	v_mfma_f32_16x16x32_bf16 v[90:93], v[160:163], v[220:223], v[90:93]
	v_mfma_f32_16x16x32_bf16 v[78:81], v[152:155], v[228:231], v[78:81]
	v_mfma_f32_16x16x32_bf16 v[74:77], v[160:163], v[228:231], v[74:77]
	v_mfma_f32_16x16x32_bf16 v[118:121], v[164:167], v[180:183], v[118:121]
	v_mfma_f32_16x16x32_bf16 v[114:117], v[172:175], v[180:183], v[114:117]
	v_mfma_f32_16x16x32_bf16 v[102:105], v[164:167], v[194:197], v[102:105]
	v_mfma_f32_16x16x32_bf16 v[98:101], v[172:175], v[194:197], v[98:101]
	v_mfma_f32_16x16x32_bf16 v[86:89], v[164:167], v[216:219], v[86:89]
	v_mfma_f32_16x16x32_bf16 v[82:85], v[172:175], v[216:219], v[82:85]
	v_mfma_f32_16x16x32_bf16 v[70:73], v[164:167], v[224:227], v[70:73]
	v_mfma_f32_16x16x32_bf16 v[66:69], v[172:175], v[224:227], v[66:69]
	v_mfma_f32_16x16x32_bf16 v[118:121], v[168:171], v[190:193], v[118:121]
	v_mfma_f32_16x16x32_bf16 v[114:117], v[176:179], v[190:193], v[114:117]
	v_mfma_f32_16x16x32_bf16 v[102:105], v[168:171], v[198:201], v[102:105]
	v_mfma_f32_16x16x32_bf16 v[98:101], v[176:179], v[198:201], v[98:101]
	v_mfma_f32_16x16x32_bf16 v[86:89], v[168:171], v[220:223], v[86:89]
	v_mfma_f32_16x16x32_bf16 v[82:85], v[176:179], v[220:223], v[82:85]
	v_mfma_f32_16x16x32_bf16 v[70:73], v[168:171], v[228:231], v[70:73]
	v_mfma_f32_16x16x32_bf16 v[66:69], v[176:179], v[228:231], v[66:69]
	s_barrier
; #define PG8_STAGE(bufoff, gbase, voff) do { _Pragma("unroll") for (int _i = 0; _i < 2; ++_i) \
;         __builtin_amdgcn_global_load_lds((const unsigned*)((const char*)(gbase) + (voff)[_i]), (PG8_LAS unsigned*)(lds + (bufoff) + ldsw + _i * 8192), 16, 0, 0); } while (0)
; #define PG8_LDA(dst, b, h) do { _Pragma("unroll") for (int m = 0; m < 4; ++m) _Pragma("unroll") for (int k = 0; k < 2; ++k) dst[m][k] = *(const PG8_LAS bf16x8*)(lds + PG8_SA(b, h) + aoff + m * 2048 + k * 1024); } while (0)
; #define PG8_MMA(ai, bj, At, Bt) do { __builtin_amdgcn_s_setprio(1); _Pragma("unroll") for (int m = 0; m < 4; ++m) _Pragma("unroll") for (int n = 0; n < 2; ++n) _Pragma("unroll") for (int k = 0; k < 2; ++k) \
;         acc[ai][bj][m][n] = __builtin_amdgcn_mfma_f32_16x16x32_bf16(Bt[n][k], At[m][k], acc[ai][bj][m][n], 0, 0, 0); __builtin_amdgcn_s_setprio(0); } while (0)
; #define PG8_WAIT_V(n) asm volatile("s_waitcnt vmcnt(" #n ")" ::: "memory")
; #define PG8_WAIT_L(n) asm volatile("s_waitcnt lgkmcnt(" #n ")" ::: "memory")
; #define PG8_BAR __builtin_amdgcn_s_barrier()
; #define PG8_SCHED __builtin_amdgcn_sched_barrier(0)
; template <class Epi, class Sched, bool ALIGN_EPI = false, bool SP2 = false>
; __device__ __forceinline__ void gemm_phase(PG8_LAS unsigned char* lds, const Gemm g, const Sched& S, const Epi& E) {
;     ...
;             PG8_LDA(At, 1, 1); PG8_STAGE(PG8_SB(1, 0), b3, voffB); PG8_STAGE(PG8_SB(1, 1), b3 + hstep, voffB); PG8_STAGE(PG8_SA(1, 0), a3, voffA);
;             PG8_WAIT_V(8); PG8_WAIT_L(0); PG8_BAR; PG8_MMA(1, 0, At, B0); PG8_MMA(1, 1, At, B1); PG8_BAR; PG8_SCHED;
	s_setprio 1
	s_add_i32 s10, s12, s60
	v_lshl_add_u64 v[184:185], v[184:185], 0, s[30:31]
	s_mov_b32 m0, s10
	ds_read_b128 v[180:183], v189 offset:49152
	ds_read_b128 v[190:193], v189 offset:50176
	ds_read_b128 v[194:197], v189 offset:51200
	ds_read_b128 v[198:201], v189 offset:52224
	ds_read_b128 v[216:219], v189 offset:53248
	ds_read_b128 v[220:223], v189 offset:54272
	ds_read_b128 v[224:227], v189 offset:55296
	ds_read_b128 v[228:231], v189 offset:56320
	global_load_lds_dwordx4 v[184:185], off
	s_add_i32 m0, s10, 0x2000
	s_add_u32 s10, s24, 0x80080
	v_lshl_add_u64 v[184:185], v[232:233], 0, s[30:31]
	s_addc_u32 s11, s25, 0
	s_add_i32 s12, s13, s60
	global_load_lds_dwordx4 v[184:185], off
	v_lshl_add_u64 v[184:185], s[10:11], 0, v[0:1]
	s_mov_b32 m0, s12
	s_nop 0
	global_load_lds_dwordx4 v[184:185], off
	v_lshl_add_u64 v[184:185], s[10:11], 0, v[142:143]
	s_add_i32 m0, s12, 0x2000
	s_nop 0
	global_load_lds_dwordx4 v[184:185], off
	v_lshl_add_u64 v[184:185], v[234:235], 0, s[30:31]
	s_mov_b32 m0, s65
	s_nop 0
	global_load_lds_dwordx4 v[184:185], off
	v_lshl_add_u64 v[184:185], v[236:237], 0, s[30:31]
	s_mov_b32 m0, s66
	s_nop 0
	global_load_lds_dwordx4 v[184:185], off
	s_waitcnt vmcnt(8)
	s_waitcnt lgkmcnt(0)
	s_setprio 0
	s_barrier
	v_mfma_f32_16x16x32_bf16 v[62:65], v[148:151], v[180:183], v[62:65]
	v_mfma_f32_16x16x32_bf16 v[58:61], v[156:159], v[180:183], v[58:61]
	v_mfma_f32_16x16x32_bf16 v[46:49], v[148:151], v[194:197], v[46:49]
	v_mfma_f32_16x16x32_bf16 v[42:45], v[156:159], v[194:197], v[42:45]
	v_mfma_f32_16x16x32_bf16 v[30:33], v[148:151], v[216:219], v[30:33]
	v_mfma_f32_16x16x32_bf16 v[26:29], v[156:159], v[216:219], v[26:29]
	v_mfma_f32_16x16x32_bf16 v[14:17], v[148:151], v[224:227], v[14:17]
	v_mfma_f32_16x16x32_bf16 v[10:13], v[156:159], v[224:227], v[10:13]
	v_mfma_f32_16x16x32_bf16 v[62:65], v[152:155], v[190:193], v[62:65]
	v_mfma_f32_16x16x32_bf16 v[58:61], v[160:163], v[190:193], v[58:61]
	v_mfma_f32_16x16x32_bf16 v[46:49], v[152:155], v[198:201], v[46:49]
	v_mfma_f32_16x16x32_bf16 v[42:45], v[160:163], v[198:201], v[42:45]
	v_mfma_f32_16x16x32_bf16 v[30:33], v[152:155], v[220:223], v[30:33]
	v_mfma_f32_16x16x32_bf16 v[26:29], v[160:163], v[220:223], v[26:29]
	v_mfma_f32_16x16x32_bf16 v[14:17], v[152:155], v[228:231], v[14:17]
	v_mfma_f32_16x16x32_bf16 v[10:13], v[160:163], v[228:231], v[10:13]
	v_mfma_f32_16x16x32_bf16 v[54:57], v[164:167], v[180:183], v[54:57]
	v_mfma_f32_16x16x32_bf16 v[50:53], v[172:175], v[180:183], v[50:53]
	v_mfma_f32_16x16x32_bf16 v[38:41], v[164:167], v[194:197], v[38:41]
	v_mfma_f32_16x16x32_bf16 v[34:37], v[172:175], v[194:197], v[34:37]
	v_mfma_f32_16x16x32_bf16 v[22:25], v[164:167], v[216:219], v[22:25]
	v_mfma_f32_16x16x32_bf16 v[18:21], v[172:175], v[216:219], v[18:21]
	v_mfma_f32_16x16x32_bf16 v[6:9], v[164:167], v[224:227], v[6:9]
	v_mfma_f32_16x16x32_bf16 v[2:5], v[172:175], v[224:227], v[2:5]
	v_mfma_f32_16x16x32_bf16 v[54:57], v[168:171], v[190:193], v[54:57]
	v_mfma_f32_16x16x32_bf16 v[50:53], v[176:179], v[190:193], v[50:53]
	v_mfma_f32_16x16x32_bf16 v[38:41], v[168:171], v[198:201], v[38:41]
	v_mfma_f32_16x16x32_bf16 v[34:37], v[176:179], v[198:201], v[34:37]
	v_mfma_f32_16x16x32_bf16 v[22:25], v[168:171], v[220:223], v[22:25]
	v_mfma_f32_16x16x32_bf16 v[18:21], v[176:179], v[220:223], v[18:21]
	v_mfma_f32_16x16x32_bf16 v[6:9], v[168:171], v[228:231], v[6:9]
	v_mfma_f32_16x16x32_bf16 v[2:5], v[176:179], v[228:231], v[2:5]
	s_barrier
	s_setprio 1
	s_add_i32 s22, s22, 2
	s_add_u32 s14, s14, 0x100
	s_addc_u32 s15, s15, 0
	s_cmp_gt_u32 s22, 29
	s_mov_b64 s[16:17], s[18:19]
	s_cbranch_scc0 .LBB0_601
; __device__ __forceinline__ unsigned cvt_pk_bf16(float lo, float hi) { unsigned r; asm volatile("v_cvt_pk_bf16_f32 %0, %1, %2" : "=v"(r) : "v"(lo), "v"(hi)); return r; }
;     __device__ __forceinline__ void operator()(const f32x4 (&acc)[2][2][4][2], const Unit& u, int wr, int wc, int fr, int fq) const {
;         const int row0 = u.pm * BM + wr * 64 + fr; const int col0 = u.pn * BM + wc * 32 + 4 * fq;
; #pragma unroll
;         for (int ai = 0; ai < 2; ++ai) {
;             u32x2 bv[4][2][2];
; #pragma unroll
;             for (int m = 0; m < 4; ++m) { const size_t off = (size_t)(row0 + ai * HALF + m * 16) * ldc + col0;
; #pragma unroll
;                 for (int bj = 0; bj < 2; ++bj)
; #pragma unroll
;                     for (int n = 0; n < 2; ++n) bv[m][bj][n] = *(const u32x2*)(xb + off + bj * HALF + n * 16); }
;             asm volatile("" ::: "memory");
; #pragma unroll
;             for (int m = 0; m < 4; ++m) {
;                 const int row = row0 + ai * HALF + m * 16;
;                 const size_t off = (size_t)row * ldc + col0;
;                 float s = 0.f;
; #pragma unroll
;                 for (int bj = 0; bj < 2; ++bj)
; #pragma unroll
;                     for (int n = 0; n < 2; ++n) {
;                         const size_t c = off + bj * HALF + n * 16;
;                         const u32x2 w0 = bv[m][bj][n];
;                         const f32x4 b = {__uint_as_float(w0.x << 16), __uint_as_float(w0.x & 0xffff0000u), __uint_as_float(w0.y << 16), __uint_as_float(w0.y & 0xffff0000u)};
;                         const f32x4 o = b + acc[ai][bj][m][n];
;                         if (fin) { *(f32x4*)(outf + c) = o; }
;                         else { u32x2 w; w.x = cvt_pk_bf16(o[0], o[1]); w.y = cvt_pk_bf16(o[2], o[3]); *(u32x2*)(xb + c) = w;
;                                s += (o[0] * o[0] + o[1] * o[1]) + (o[2] * o[2] + o[3] * o[3]); }
;                     }
;                 if (!fin) { s += __shfl_xor(s, 16); s += __shfl_xor(s, 32); if (fq == 0) unsafeAtomicAdd(ssq + row, s); }
	v_lshl_or_b32 v148, s2, 8, v188
	v_lshl_add_u32 v152, s4, 8, v186
	v_ashrrev_i32_e32 v149, 31, v148
	v_lshlrev_b64 v[190:191], 1, v[148:149]
	v_ashrrev_i32_e32 v153, 31, v152
	v_lshl_add_u64 v[150:151], s[48:49], 0, v[190:191]
	v_lshlrev_b64 v[154:155], 12, v[152:153]
	v_lshl_add_u64 v[156:157], v[150:151], 0, v[154:155]
	global_load_dwordx2 v[192:193], v[156:157], off
	global_load_dwordx2 v[194:195], v[156:157], off offset:32
	global_load_dwordx2 v[196:197], v[156:157], off offset:256
	global_load_dwordx2 v[198:199], v[156:157], off offset:288
	v_or_b32_e32 v184, 16, v152
	v_ashrrev_i32_e32 v185, 31, v184
	v_lshlrev_b64 v[156:157], 12, v[184:185]
	v_or_b32_e32 v174, 32, v152
	v_lshl_add_u64 v[156:157], v[150:151], 0, v[156:157]
	v_ashrrev_i32_e32 v175, 31, v174
	global_load_dwordx2 v[182:183], v[156:157], off
	global_load_dwordx2 v[180:181], v[156:157], off offset:32
	global_load_dwordx2 v[178:179], v[156:157], off offset:256
	global_load_dwordx2 v[176:177], v[156:157], off offset:288
	v_lshlrev_b64 v[156:157], 12, v[174:175]
	v_or_b32_e32 v158, 48, v152
	v_lshl_add_u64 v[156:157], v[150:151], 0, v[156:157]
	v_ashrrev_i32_e32 v159, 31, v158
	global_load_dwordx2 v[172:173], v[156:157], off
	global_load_dwordx2 v[170:171], v[156:157], off offset:32
	global_load_dwordx2 v[166:167], v[156:157], off offset:256
	global_load_dwordx2 v[162:163], v[156:157], off offset:288
	v_lshlrev_b64 v[156:157], 12, v[158:159]
	v_lshl_add_u64 v[156:157], v[150:151], 0, v[156:157]
	global_load_dwordx2 v[168:169], v[156:157], off
	global_load_dwordx2 v[164:165], v[156:157], off offset:32
	global_load_dwordx2 v[160:161], v[156:157], off offset:256
	s_nop 0
	global_load_dwordx2 v[156:157], v[156:157], off offset:288
	s_waitcnt vmcnt(0)
	v_lshlrev_b32_e32 v200, 16, v192
	v_and_b32_e32 v201, 0xffff0000, v192
	v_lshlrev_b32_e32 v192, 16, v193
	v_and_b32_e32 v193, 0xffff0000, v193
	v_pk_add_f32 v[126:127], v[126:127], v[200:201]
	v_pk_add_f32 v[128:129], v[128:129], v[192:193]
	v_cvt_pk_bf16_f32 v192, v126, v127
	v_mul_f32_e32 v127, v127, v127
	v_lshl_add_u64 v[200:201], s[48:49], 0, v[154:155]
	v_fmac_f32_e32 v127, v126, v126
	v_mul_f32_e32 v126, v129, v129
	v_lshl_add_u64 v[190:191], v[200:201], 0, v[190:191]
	v_fmac_f32_e32 v126, v128, v128
	v_cvt_pk_bf16_f32 v193, v128, v129
	global_store_dwordx2 v[190:191], v[192:193], off
	v_add_f32_e32 v192, v127, v126
	v_lshlrev_b32_e32 v126, 16, v194
	v_and_b32_e32 v127, 0xffff0000, v194
	v_lshlrev_b32_e32 v128, 16, v195
	v_and_b32_e32 v129, 0xffff0000, v195
	v_pk_add_f32 v[122:123], v[122:123], v[126:127]
	v_pk_add_f32 v[124:125], v[124:125], v[128:129]
	v_cvt_pk_bf16_f32 v126, v122, v123
	v_mul_f32_e32 v123, v123, v123
	v_fmac_f32_e32 v123, v122, v122
	v_mul_f32_e32 v122, v125, v125
	v_fmac_f32_e32 v122, v124, v124
	v_add_f32_e32 v122, v123, v122
	v_cvt_pk_bf16_f32 v127, v124, v125
	global_store_dwordx2 v[190:191], v[126:127], off offset:32
	v_add_f32_e32 v126, v192, v122
	v_lshlrev_b32_e32 v122, 16, v196
	v_and_b32_e32 v123, 0xffff0000, v196
	v_lshlrev_b32_e32 v124, 16, v197
	v_and_b32_e32 v125, 0xffff0000, v197
	v_pk_add_f32 v[118:119], v[118:119], v[122:123]
	v_pk_add_f32 v[120:121], v[120:121], v[124:125]
	v_cvt_pk_bf16_f32 v122, v118, v119
	v_mul_f32_e32 v119, v119, v119
	v_fmac_f32_e32 v119, v118, v118
	v_mul_f32_e32 v118, v121, v121
	v_fmac_f32_e32 v118, v120, v120
	v_add_f32_e32 v118, v119, v118
	v_cvt_pk_bf16_f32 v123, v120, v121
	global_store_dwordx2 v[190:191], v[122:123], off offset:256
	v_add_f32_e32 v122, v126, v118
	v_lshlrev_b32_e32 v118, 16, v198
	v_and_b32_e32 v119, 0xffff0000, v198
	v_lshlrev_b32_e32 v120, 16, v199
	v_and_b32_e32 v121, 0xffff0000, v199
	v_pk_add_f32 v[114:115], v[114:115], v[118:119]
	v_pk_add_f32 v[116:117], v[116:117], v[120:121]
	v_cvt_pk_bf16_f32 v118, v114, v115
	v_mul_f32_e32 v115, v115, v115
	v_fmac_f32_e32 v115, v114, v114
	v_mul_f32_e32 v114, v117, v117
	v_cvt_pk_bf16_f32 v119, v116, v117
	v_fmac_f32_e32 v114, v116, v116
	v_and_b32_e32 v116, 64, v208
	v_add_f32_e32 v114, v115, v114
	v_xor_b32_e32 v115, 16, v208
	v_add_u32_e32 v117, 64, v116
	v_cmp_lt_i32_e32 vcc, v115, v117
	v_add_f32_e32 v114, v122, v114
	global_store_dwordx2 v[190:191], v[118:119], off offset:288
	v_cndmask_b32_e32 v115, v208, v115, vcc
	v_lshlrev_b32_e32 v116, 2, v115
	ds_bpermute_b32 v115, v116, v114
	s_waitcnt lgkmcnt(0)
	v_add_f32_e32 v118, v114, v115
	v_xor_b32_e32 v114, 32, v208
	v_cmp_lt_i32_e32 vcc, v114, v117
	s_nop 1
	v_cndmask_b32_e32 v114, v208, v114, vcc
	v_lshlrev_b32_e32 v117, 2, v114
	ds_bpermute_b32 v119, v117, v118
	v_lshl_add_u64 v[114:115], v[152:153], 2, s[50:51]
	s_and_saveexec_b64 s[16:17], s[42:43]
	s_cbranch_execz .LBB0_604
	s_waitcnt lgkmcnt(0)
	v_add_f32_e32 v118, v118, v119
	global_atomic_add_f32 v[114:115], v118, off

; #define PG8_STAGE(bufoff, gbase, voff) do { _Pragma("unroll") for (int _i = 0; _i < 2; ++_i) \
;         __builtin_amdgcn_global_load_lds((const unsigned*)((const char*)(gbase) + (voff)[_i]), (PG8_LAS unsigned*)(lds + (bufoff) + ldsw + _i * 8192), 16, 0, 0); } while (0)
; #define PG8_LDA(dst, b, h) do { _Pragma("unroll") for (int m = 0; m < 4; ++m) _Pragma("unroll") for (int k = 0; k < 2; ++k) dst[m][k] = *(const PG8_LAS bf16x8*)(lds + PG8_SA(b, h) + aoff + m * 2048 + k * 1024); } while (0)
; #define PG8_LDB(dst, b, h) do { _Pragma("unroll") for (int n = 0; n < 2; ++n) _Pragma("unroll") for (int k = 0; k < 2; ++k) dst[n][k] = *(const PG8_LAS bf16x8*)(lds + PG8_SB(b, h) + boff + n * 2048 + k * 1024); } while (0)
; #define PG8_MMA(ai, bj, At, Bt) do { __builtin_amdgcn_s_setprio(1); _Pragma("unroll") for (int m = 0; m < 4; ++m) _Pragma("unroll") for (int n = 0; n < 2; ++n) _Pragma("unroll") for (int k = 0; k < 2; ++k) \
;         acc[ai][bj][m][n] = __builtin_amdgcn_mfma_f32_16x16x32_bf16(Bt[n][k], At[m][k], acc[ai][bj][m][n], 0, 0, 0); __builtin_amdgcn_s_setprio(0); } while (0)
; #define PG8_WAIT_V(n) asm volatile("s_waitcnt vmcnt(" #n ")" ::: "memory")
; #define PG8_WAIT_L(n) asm volatile("s_waitcnt lgkmcnt(" #n ")" ::: "memory")
; template <class Epi, class Sched, bool ALIGN_EPI = false, bool SP2 = false>
; __device__ __forceinline__ void gemm_phase(PG8_LAS unsigned char* lds, const Gemm g, const Sched& S, const Epi& E) {
;     ...
;             const bool last = (t == nt - 2);
;             const char* a1 = cA + (size_t)(t + 1) * kstep;
;             const char* a2 = last ? nA : cA + (size_t)(t + 2) * kstep; const char* b2 = last ? nB : cB + (size_t)(t + 2) * kstep;
;             const char* a3 = a2 + kstep; const char* b3 = b2 + kstep;
;             if (last && has_next) S.a_ready(nxt);
;             if constexpr (SP2) {
;             PG8_LDB(B0, 0, 0); PG8_LDB(B1, 0, 1); PG8_SCHED; PG8_LDA(At, 0, 0); PG8_STAGE(PG8_SA(1, 1), a1 + hstep, voffA);
;             PG8_WAIT_V(8); PG8_WAIT_L(0); PG8_BAR; PG8_MMA(0, 0, At, B0); PG8_MMA(0, 1, At, B1); PG8_BAR; PG8_SCHED;
;             PG8_LDA(At, 0, 1); PG8_STAGE(PG8_SB(0, 0), b2, voffB); PG8_STAGE(PG8_SB(0, 1), b2 + hstep, voffB); PG8_STAGE(PG8_SA(0, 0), a2, voffA);
;             PG8_WAIT_V(8); PG8_WAIT_L(0); PG8_BAR; PG8_MMA(1, 0, At, B0); PG8_MMA(1, 1, At, B1); PG8_BAR; PG8_SCHED;
.LBB0_686:
	s_add_u32 s10, s16, 0xfff80080
	s_addc_u32 s11, s17, -1
	s_add_i32 s12, 0, 0x10000
	s_cmp_eq_u32 s22, 28
	s_cselect_b32 s25, s5, s11
	s_cselect_b32 s24, s7, s10
	v_add_u32_e32 v160, s12, v163
	s_cselect_b32 s19, s8, s15
	s_cselect_b32 s18, s9, s14
	s_add_i32 s13, 0, 0x14000
	ds_read_b128 v[152:155], v160
	ds_read_b128 v[156:159], v160 offset:1024
	ds_read_b128 v[166:169], v160 offset:2048
	ds_read_b128 v[170:173], v160 offset:3072
	v_add_u32_e32 v160, s13, v163
	ds_read_b128 v[174:177], v160
	ds_read_b128 v[178:181], v160 offset:1024
	ds_read_b128 v[182:185], v160 offset:2048
	ds_read_b128 v[186:189], v160 offset:3072
	v_lshl_add_u64 v[160:161], s[16:17], 0, v[148:149]
	s_add_i32 m0, s59, 0xc000
	ds_read_b128 v[190:193], v165
	ds_read_b128 v[194:197], v165 offset:1024
	ds_read_b128 v[198:201], v165 offset:2048
	ds_read_b128 v[216:219], v165 offset:3072
	ds_read_b128 v[220:223], v165 offset:4096
	ds_read_b128 v[224:227], v165 offset:5120
	ds_read_b128 v[228:231], v165 offset:6144
	ds_read_b128 v[232:235], v165 offset:7168
	global_load_lds_dwordx4 v[160:161], off
	v_lshl_add_u64 v[160:161], s[16:17], 0, v[150:151]
	s_add_i32 m0, s59, 0xe000
	s_nop 0
	global_load_lds_dwordx4 v[160:161], off
	s_waitcnt vmcnt(8)
	s_waitcnt lgkmcnt(0)
	s_setprio 0
	s_barrier
	v_mfma_f32_16x16x32_bf16 v[126:129], v[152:155], v[190:193], v[126:129]
	v_mfma_f32_16x16x32_bf16 v[122:125], v[166:169], v[190:193], v[122:125]
	v_mfma_f32_16x16x32_bf16 v[110:113], v[152:155], v[198:201], v[110:113]
	v_mfma_f32_16x16x32_bf16 v[106:109], v[166:169], v[198:201], v[106:109]
	v_mfma_f32_16x16x32_bf16 v[94:97], v[152:155], v[220:223], v[94:97]
	v_mfma_f32_16x16x32_bf16 v[90:93], v[166:169], v[220:223], v[90:93]
	v_mfma_f32_16x16x32_bf16 v[78:81], v[152:155], v[228:231], v[78:81]
	v_mfma_f32_16x16x32_bf16 v[74:77], v[166:169], v[228:231], v[74:77]
	v_mfma_f32_16x16x32_bf16 v[126:129], v[156:159], v[194:197], v[126:129]
	v_mfma_f32_16x16x32_bf16 v[122:125], v[170:173], v[194:197], v[122:125]
	v_mfma_f32_16x16x32_bf16 v[110:113], v[156:159], v[216:219], v[110:113]
	v_mfma_f32_16x16x32_bf16 v[106:109], v[170:173], v[216:219], v[106:109]
	v_mfma_f32_16x16x32_bf16 v[94:97], v[156:159], v[224:227], v[94:97]
	v_mfma_f32_16x16x32_bf16 v[90:93], v[170:173], v[224:227], v[90:93]
	v_mfma_f32_16x16x32_bf16 v[78:81], v[156:159], v[232:235], v[78:81]
	v_mfma_f32_16x16x32_bf16 v[74:77], v[170:173], v[232:235], v[74:77]
	v_mfma_f32_16x16x32_bf16 v[118:121], v[174:177], v[190:193], v[118:121]
	v_mfma_f32_16x16x32_bf16 v[114:117], v[182:185], v[190:193], v[114:117]
	v_mfma_f32_16x16x32_bf16 v[102:105], v[174:177], v[198:201], v[102:105]
	v_mfma_f32_16x16x32_bf16 v[98:101], v[182:185], v[198:201], v[98:101]
	v_mfma_f32_16x16x32_bf16 v[86:89], v[174:177], v[220:223], v[86:89]
	v_mfma_f32_16x16x32_bf16 v[82:85], v[182:185], v[220:223], v[82:85]
	v_mfma_f32_16x16x32_bf16 v[70:73], v[174:177], v[228:231], v[70:73]
	v_mfma_f32_16x16x32_bf16 v[66:69], v[182:185], v[228:231], v[66:69]
	v_mfma_f32_16x16x32_bf16 v[118:121], v[178:181], v[194:197], v[118:121]
	v_mfma_f32_16x16x32_bf16 v[114:117], v[186:189], v[194:197], v[114:117]
	v_mfma_f32_16x16x32_bf16 v[102:105], v[178:181], v[216:219], v[102:105]
	v_mfma_f32_16x16x32_bf16 v[98:101], v[186:189], v[216:219], v[98:101]
	v_mfma_f32_16x16x32_bf16 v[86:89], v[178:181], v[224:227], v[86:89]
	v_mfma_f32_16x16x32_bf16 v[82:85], v[186:189], v[224:227], v[82:85]
	v_mfma_f32_16x16x32_bf16 v[70:73], v[178:181], v[232:235], v[70:73]
	v_mfma_f32_16x16x32_bf16 v[66:69], v[186:189], v[232:235], v[66:69]
	s_barrier
	s_setprio 1
	s_add_i32 s10, s12, s58
	v_lshl_add_u64 v[160:161], s[18:19], 0, v[0:1]
	s_mov_b32 m0, s10
	ds_read_b128 v[190:193], v165 offset:16384
	ds_read_b128 v[194:197], v165 offset:17408
	ds_read_b128 v[198:201], v165 offset:18432
	ds_read_b128 v[216:219], v165 offset:19456
	ds_read_b128 v[220:223], v165 offset:20480
	ds_read_b128 v[224:227], v165 offset:21504
	ds_read_b128 v[228:231], v165 offset:22528
	ds_read_b128 v[232:235], v165 offset:23552
	global_load_lds_dwordx4 v[160:161], off
	s_add_i32 m0, s10, 0x2000
	s_add_u32 s10, s18, 0x80000
	v_lshl_add_u64 v[236:237], s[18:19], 0, v[142:143]
	s_addc_u32 s11, s19, 0
	s_add_i32 s12, s13, s58
	global_load_lds_dwordx4 v[236:237], off
	v_lshl_add_u64 v[238:239], s[10:11], 0, v[0:1]
	s_mov_b32 m0, s12
	v_lshl_add_u64 v[240:241], s[24:25], 0, v[144:145]
	global_load_lds_dwordx4 v[238:239], off
	v_lshl_add_u64 v[238:239], s[10:11], 0, v[142:143]
	s_add_i32 m0, s12, 0x2000
	s_nop 0
	global_load_lds_dwordx4 v[238:239], off
	v_lshl_add_u64 v[238:239], s[24:25], 0, v[146:147]
	s_mov_b32 m0, s59
	s_nop 0
	global_load_lds_dwordx4 v[238:239], off
	s_mov_b32 m0, s60
	s_nop 0
	global_load_lds_dwordx4 v[240:241], off
	s_waitcnt vmcnt(8)
	s_waitcnt lgkmcnt(0)
	s_setprio 0
	s_barrier
; #define PG8_STAGE(bufoff, gbase, voff) do { _Pragma("unroll") for (int _i = 0; _i < 2; ++_i) \
;         __builtin_amdgcn_global_load_lds((const unsigned*)((const char*)(gbase) + (voff)[_i]), (PG8_LAS unsigned*)(lds + (bufoff) + ldsw + _i * 8192), 16, 0, 0); } while (0)
; #define PG8_LDA(dst, b, h) do { _Pragma("unroll") for (int m = 0; m < 4; ++m) _Pragma("unroll") for (int k = 0; k < 2; ++k) dst[m][k] = *(const PG8_LAS bf16x8*)(lds + PG8_SA(b, h) + aoff + m * 2048 + k * 1024); } while (0)
; #define PG8_LDB(dst, b, h) do { _Pragma("unroll") for (int n = 0; n < 2; ++n) _Pragma("unroll") for (int k = 0; k < 2; ++k) dst[n][k] = *(const PG8_LAS bf16x8*)(lds + PG8_SB(b, h) + boff + n * 2048 + k * 1024); } while (0)
; #define PG8_MMA(ai, bj, At, Bt) do { __builtin_amdgcn_s_setprio(1); _Pragma("unroll") for (int m = 0; m < 4; ++m) _Pragma("unroll") for (int n = 0; n < 2; ++n) _Pragma("unroll") for (int k = 0; k < 2; ++k) \
;         acc[ai][bj][m][n] = __builtin_amdgcn_mfma_f32_16x16x32_bf16(Bt[n][k], At[m][k], acc[ai][bj][m][n], 0, 0, 0); __builtin_amdgcn_s_setprio(0); } while (0)
; #define PG8_WAIT_V(n) asm volatile("s_waitcnt vmcnt(" #n ")" ::: "memory")
; #define PG8_WAIT_L(n) asm volatile("s_waitcnt lgkmcnt(" #n ")" ::: "memory")
; #define PG8_BAR __builtin_amdgcn_s_barrier()
; #define PG8_SCHED __builtin_amdgcn_sched_barrier(0)
; template <class Epi, class Sched, bool ALIGN_EPI = false, bool SP2 = false>
; __device__ __forceinline__ void gemm_phase(PG8_LAS unsigned char* lds, const Gemm g, const Sched& S, const Epi& E) {
;     ...
;             PG8_WAIT_V(8); PG8_WAIT_L(0); PG8_BAR; PG8_MMA(1, 0, At, B0); PG8_MMA(1, 1, At, B1); PG8_BAR; PG8_SCHED;
;             PG8_LDB(B0, 1, 0); PG8_LDB(B1, 1, 1); PG8_SCHED; PG8_LDA(At, 1, 0); PG8_STAGE(PG8_SA(0, 1), a2 + hstep, voffA);
;             PG8_WAIT_V(8); PG8_WAIT_L(0); PG8_BAR; PG8_MMA(0, 0, At, B0); PG8_MMA(0, 1, At, B1); PG8_BAR; PG8_SCHED;
	v_mfma_f32_16x16x32_bf16 v[62:65], v[152:155], v[190:193], v[62:65]
	v_mfma_f32_16x16x32_bf16 v[58:61], v[166:169], v[190:193], v[58:61]
	v_mfma_f32_16x16x32_bf16 v[46:49], v[152:155], v[198:201], v[46:49]
	v_mfma_f32_16x16x32_bf16 v[42:45], v[166:169], v[198:201], v[42:45]
	v_mfma_f32_16x16x32_bf16 v[30:33], v[152:155], v[220:223], v[30:33]
	v_mfma_f32_16x16x32_bf16 v[26:29], v[166:169], v[220:223], v[26:29]
	v_mfma_f32_16x16x32_bf16 v[14:17], v[152:155], v[228:231], v[14:17]
	v_mfma_f32_16x16x32_bf16 v[10:13], v[166:169], v[228:231], v[10:13]
	v_mfma_f32_16x16x32_bf16 v[62:65], v[156:159], v[194:197], v[62:65]
	v_mfma_f32_16x16x32_bf16 v[58:61], v[170:173], v[194:197], v[58:61]
	v_mfma_f32_16x16x32_bf16 v[46:49], v[156:159], v[216:219], v[46:49]
	v_mfma_f32_16x16x32_bf16 v[42:45], v[170:173], v[216:219], v[42:45]
	v_mfma_f32_16x16x32_bf16 v[30:33], v[156:159], v[224:227], v[30:33]
	v_mfma_f32_16x16x32_bf16 v[26:29], v[170:173], v[224:227], v[26:29]
	v_mfma_f32_16x16x32_bf16 v[14:17], v[156:159], v[232:235], v[14:17]
	v_mfma_f32_16x16x32_bf16 v[10:13], v[170:173], v[232:235], v[10:13]
	v_mfma_f32_16x16x32_bf16 v[54:57], v[174:177], v[190:193], v[54:57]
	v_mfma_f32_16x16x32_bf16 v[50:53], v[182:185], v[190:193], v[50:53]
	v_mfma_f32_16x16x32_bf16 v[38:41], v[174:177], v[198:201], v[38:41]
	v_mfma_f32_16x16x32_bf16 v[34:37], v[182:185], v[198:201], v[34:37]
	v_mfma_f32_16x16x32_bf16 v[22:25], v[174:177], v[220:223], v[22:25]
	v_mfma_f32_16x16x32_bf16 v[18:21], v[182:185], v[220:223], v[18:21]
	v_mfma_f32_16x16x32_bf16 v[6:9], v[174:177], v[228:231], v[6:9]
	v_mfma_f32_16x16x32_bf16 v[2:5], v[182:185], v[228:231], v[2:5]
	v_mfma_f32_16x16x32_bf16 v[54:57], v[178:181], v[194:197], v[54:57]
	v_mfma_f32_16x16x32_bf16 v[50:53], v[186:189], v[194:197], v[50:53]
	v_mfma_f32_16x16x32_bf16 v[38:41], v[178:181], v[216:219], v[38:41]
	v_mfma_f32_16x16x32_bf16 v[34:37], v[186:189], v[216:219], v[34:37]
	v_mfma_f32_16x16x32_bf16 v[22:25], v[178:181], v[224:227], v[22:25]
	v_mfma_f32_16x16x32_bf16 v[18:21], v[186:189], v[224:227], v[18:21]
	v_mfma_f32_16x16x32_bf16 v[6:9], v[178:181], v[232:235], v[6:9]
	v_mfma_f32_16x16x32_bf16 v[2:5], v[186:189], v[232:235], v[2:5]
	s_barrier
	s_setprio 1
	s_add_i32 s12, 0, 0x18000
	s_add_i32 s13, 0, 0x1c000
	v_add_u32_e32 v170, s12, v163
	v_add_u32_e32 v186, s13, v163
	ds_read_b128 v[152:155], v170
	ds_read_b128 v[156:159], v170 offset:1024
	ds_read_b128 v[166:169], v170 offset:2048
	ds_read_b128 v[170:173], v170 offset:3072
	ds_read_b128 v[174:177], v186
	ds_read_b128 v[178:181], v186 offset:1024
	ds_read_b128 v[182:185], v186 offset:2048
	ds_read_b128 v[186:189], v186 offset:3072
	s_add_u32 s10, s24, 0x80000
	s_addc_u32 s11, s25, 0
	s_mov_b32 m0, s61
	v_lshl_add_u64 v[242:243], s[10:11], 0, v[146:147]
	ds_read_b128 v[190:193], v165 offset:32768
	ds_read_b128 v[194:197], v165 offset:33792
	ds_read_b128 v[198:201], v165 offset:34816
	ds_read_b128 v[216:219], v165 offset:35840
	ds_read_b128 v[220:223], v165 offset:36864
	ds_read_b128 v[224:227], v165 offset:37888
	ds_read_b128 v[228:231], v165 offset:38912
	ds_read_b128 v[232:235], v165 offset:39936
	global_load_lds_dwordx4 v[242:243], off
	v_lshl_add_u64 v[242:243], s[10:11], 0, v[144:145]
	s_mov_b32 m0, s62
	s_nop 0
	global_load_lds_dwordx4 v[242:243], off
	s_waitcnt vmcnt(8)
	s_waitcnt lgkmcnt(0)
	s_setprio 0
	s_barrier
	v_mfma_f32_16x16x32_bf16 v[126:129], v[152:155], v[190:193], v[126:129]
	v_mfma_f32_16x16x32_bf16 v[122:125], v[166:169], v[190:193], v[122:125]
	v_mfma_f32_16x16x32_bf16 v[110:113], v[152:155], v[198:201], v[110:113]
	v_mfma_f32_16x16x32_bf16 v[106:109], v[166:169], v[198:201], v[106:109]
	v_mfma_f32_16x16x32_bf16 v[94:97], v[152:155], v[220:223], v[94:97]
	v_mfma_f32_16x16x32_bf16 v[90:93], v[166:169], v[220:223], v[90:93]
	v_mfma_f32_16x16x32_bf16 v[78:81], v[152:155], v[228:231], v[78:81]
	v_mfma_f32_16x16x32_bf16 v[74:77], v[166:169], v[228:231], v[74:77]
	v_mfma_f32_16x16x32_bf16 v[126:129], v[156:159], v[194:197], v[126:129]
	v_mfma_f32_16x16x32_bf16 v[122:125], v[170:173], v[194:197], v[122:125]
	v_mfma_f32_16x16x32_bf16 v[110:113], v[156:159], v[216:219], v[110:113]
	v_mfma_f32_16x16x32_bf16 v[106:109], v[170:173], v[216:219], v[106:109]
	v_mfma_f32_16x16x32_bf16 v[94:97], v[156:159], v[224:227], v[94:97]
	v_mfma_f32_16x16x32_bf16 v[90:93], v[170:173], v[224:227], v[90:93]
	v_mfma_f32_16x16x32_bf16 v[78:81], v[156:159], v[232:235], v[78:81]
	v_mfma_f32_16x16x32_bf16 v[74:77], v[170:173], v[232:235], v[74:77]
	v_mfma_f32_16x16x32_bf16 v[118:121], v[174:177], v[190:193], v[118:121]
	v_mfma_f32_16x16x32_bf16 v[114:117], v[182:185], v[190:193], v[114:117]
	v_mfma_f32_16x16x32_bf16 v[102:105], v[174:177], v[198:201], v[102:105]
	v_mfma_f32_16x16x32_bf16 v[98:101], v[182:185], v[198:201], v[98:101]
	v_mfma_f32_16x16x32_bf16 v[86:89], v[174:177], v[220:223], v[86:89]
	v_mfma_f32_16x16x32_bf16 v[82:85], v[182:185], v[220:223], v[82:85]
	v_mfma_f32_16x16x32_bf16 v[70:73], v[174:177], v[228:231], v[70:73]
	v_mfma_f32_16x16x32_bf16 v[66:69], v[182:185], v[228:231], v[66:69]
	v_mfma_f32_16x16x32_bf16 v[118:121], v[178:181], v[194:197], v[118:121]
	v_mfma_f32_16x16x32_bf16 v[114:117], v[186:189], v[194:197], v[114:117]
	v_mfma_f32_16x16x32_bf16 v[102:105], v[178:181], v[216:219], v[102:105]
	v_mfma_f32_16x16x32_bf16 v[98:101], v[186:189], v[216:219], v[98:101]
	v_mfma_f32_16x16x32_bf16 v[86:89], v[178:181], v[224:227], v[86:89]
	v_mfma_f32_16x16x32_bf16 v[82:85], v[186:189], v[224:227], v[82:85]
	v_mfma_f32_16x16x32_bf16 v[70:73], v[178:181], v[232:235], v[70:73]
	v_mfma_f32_16x16x32_bf16 v[66:69], v[186:189], v[232:235], v[66:69]
	s_barrier
; #define PG8_STAGE(bufoff, gbase, voff) do { _Pragma("unroll") for (int _i = 0; _i < 2; ++_i) \
;         __builtin_amdgcn_global_load_lds((const unsigned*)((const char*)(gbase) + (voff)[_i]), (PG8_LAS unsigned*)(lds + (bufoff) + ldsw + _i * 8192), 16, 0, 0); } while (0)
; #define PG8_LDA(dst, b, h) do { _Pragma("unroll") for (int m = 0; m < 4; ++m) _Pragma("unroll") for (int k = 0; k < 2; ++k) dst[m][k] = *(const PG8_LAS bf16x8*)(lds + PG8_SA(b, h) + aoff + m * 2048 + k * 1024); } while (0)
; #define PG8_MMA(ai, bj, At, Bt) do { __builtin_amdgcn_s_setprio(1); _Pragma("unroll") for (int m = 0; m < 4; ++m) _Pragma("unroll") for (int n = 0; n < 2; ++n) _Pragma("unroll") for (int k = 0; k < 2; ++k) \
;         acc[ai][bj][m][n] = __builtin_amdgcn_mfma_f32_16x16x32_bf16(Bt[n][k], At[m][k], acc[ai][bj][m][n], 0, 0, 0); __builtin_amdgcn_s_setprio(0); } while (0)
; #define PG8_WAIT_V(n) asm volatile("s_waitcnt vmcnt(" #n ")" ::: "memory")
; #define PG8_WAIT_L(n) asm volatile("s_waitcnt lgkmcnt(" #n ")" ::: "memory")
; #define PG8_BAR __builtin_amdgcn_s_barrier()
; #define PG8_SCHED __builtin_amdgcn_sched_barrier(0)
; template <class Epi, class Sched, bool ALIGN_EPI = false, bool SP2 = false>
; __device__ __forceinline__ void gemm_phase(PG8_LAS unsigned char* lds, const Gemm g, const Sched& S, const Epi& E) {
;     ...
;             PG8_LDA(At, 1, 1); PG8_STAGE(PG8_SB(1, 0), b3, voffB); PG8_STAGE(PG8_SB(1, 1), b3 + hstep, voffB); PG8_STAGE(PG8_SA(1, 0), a3, voffA);
;             PG8_WAIT_V(8); PG8_WAIT_L(0); PG8_BAR; PG8_MMA(1, 0, At, B0); PG8_MMA(1, 1, At, B1); PG8_BAR; PG8_SCHED;
;     ...
;         if constexpr (ALIGN_EPI) { if (wr == 0) PG8_BAR; }
	s_setprio 1
	s_add_i32 s10, s12, s58
	v_lshl_add_u64 v[160:161], v[160:161], 0, s[30:31]
	s_mov_b32 m0, s10
	ds_read_b128 v[190:193], v165 offset:49152
	ds_read_b128 v[194:197], v165 offset:50176
	ds_read_b128 v[198:201], v165 offset:51200
	ds_read_b128 v[216:219], v165 offset:52224
	ds_read_b128 v[220:223], v165 offset:53248
	ds_read_b128 v[224:227], v165 offset:54272
	ds_read_b128 v[228:231], v165 offset:55296
	ds_read_b128 v[232:235], v165 offset:56320
	global_load_lds_dwordx4 v[160:161], off
	s_add_i32 m0, s10, 0x2000
	s_add_u32 s10, s18, 0x80080
	v_lshl_add_u64 v[160:161], v[236:237], 0, s[30:31]
	s_addc_u32 s11, s19, 0
	s_add_i32 s12, s13, s58
	global_load_lds_dwordx4 v[160:161], off
	v_lshl_add_u64 v[160:161], s[10:11], 0, v[0:1]
	s_mov_b32 m0, s12
	s_nop 0
	global_load_lds_dwordx4 v[160:161], off
	v_lshl_add_u64 v[160:161], s[10:11], 0, v[142:143]
	s_add_i32 m0, s12, 0x2000
	s_nop 0
	global_load_lds_dwordx4 v[160:161], off
	v_lshl_add_u64 v[160:161], v[238:239], 0, s[30:31]
	s_mov_b32 m0, s63
	s_nop 0
	global_load_lds_dwordx4 v[160:161], off
	v_lshl_add_u64 v[160:161], v[240:241], 0, s[30:31]
	s_mov_b32 m0, s64
	s_nop 0
	global_load_lds_dwordx4 v[160:161], off
	s_waitcnt vmcnt(8)
	s_waitcnt lgkmcnt(0)
	s_setprio 0
	s_barrier
	v_mfma_f32_16x16x32_bf16 v[62:65], v[152:155], v[190:193], v[62:65]
	v_mfma_f32_16x16x32_bf16 v[58:61], v[166:169], v[190:193], v[58:61]
	v_mfma_f32_16x16x32_bf16 v[46:49], v[152:155], v[198:201], v[46:49]
	v_mfma_f32_16x16x32_bf16 v[42:45], v[166:169], v[198:201], v[42:45]
	v_mfma_f32_16x16x32_bf16 v[30:33], v[152:155], v[220:223], v[30:33]
	v_mfma_f32_16x16x32_bf16 v[26:29], v[166:169], v[220:223], v[26:29]
	v_mfma_f32_16x16x32_bf16 v[14:17], v[152:155], v[228:231], v[14:17]
	v_mfma_f32_16x16x32_bf16 v[10:13], v[166:169], v[228:231], v[10:13]
	v_mfma_f32_16x16x32_bf16 v[62:65], v[156:159], v[194:197], v[62:65]
	v_mfma_f32_16x16x32_bf16 v[58:61], v[170:173], v[194:197], v[58:61]
	v_mfma_f32_16x16x32_bf16 v[46:49], v[156:159], v[216:219], v[46:49]
	v_mfma_f32_16x16x32_bf16 v[42:45], v[170:173], v[216:219], v[42:45]
	v_mfma_f32_16x16x32_bf16 v[30:33], v[156:159], v[224:227], v[30:33]
	v_mfma_f32_16x16x32_bf16 v[26:29], v[170:173], v[224:227], v[26:29]
	v_mfma_f32_16x16x32_bf16 v[14:17], v[156:159], v[232:235], v[14:17]
	v_mfma_f32_16x16x32_bf16 v[10:13], v[170:173], v[232:235], v[10:13]
	v_mfma_f32_16x16x32_bf16 v[54:57], v[174:177], v[190:193], v[54:57]
	v_mfma_f32_16x16x32_bf16 v[50:53], v[182:185], v[190:193], v[50:53]
	v_mfma_f32_16x16x32_bf16 v[38:41], v[174:177], v[198:201], v[38:41]
	v_mfma_f32_16x16x32_bf16 v[34:37], v[182:185], v[198:201], v[34:37]
	v_mfma_f32_16x16x32_bf16 v[22:25], v[174:177], v[220:223], v[22:25]
	v_mfma_f32_16x16x32_bf16 v[18:21], v[182:185], v[220:223], v[18:21]
	v_mfma_f32_16x16x32_bf16 v[6:9], v[174:177], v[228:231], v[6:9]
	v_mfma_f32_16x16x32_bf16 v[2:5], v[182:185], v[228:231], v[2:5]
	v_mfma_f32_16x16x32_bf16 v[54:57], v[178:181], v[194:197], v[54:57]
	v_mfma_f32_16x16x32_bf16 v[50:53], v[186:189], v[194:197], v[50:53]
	v_mfma_f32_16x16x32_bf16 v[38:41], v[178:181], v[216:219], v[38:41]
	v_mfma_f32_16x16x32_bf16 v[34:37], v[186:189], v[216:219], v[34:37]
	v_mfma_f32_16x16x32_bf16 v[22:25], v[178:181], v[224:227], v[22:25]
	v_mfma_f32_16x16x32_bf16 v[18:21], v[186:189], v[224:227], v[18:21]
	v_mfma_f32_16x16x32_bf16 v[6:9], v[178:181], v[232:235], v[6:9]
	v_mfma_f32_16x16x32_bf16 v[2:5], v[186:189], v[232:235], v[2:5]
	s_barrier
	s_setprio 1
	s_add_i32 s22, s22, 2
	s_add_u32 s16, s16, 0x100
	s_addc_u32 s17, s17, 0
	s_add_u32 s14, s14, 0x100
	s_addc_u32 s15, s15, 0
	s_cmp_gt_u32 s22, 29
	s_cbranch_scc0 .LBB0_686
	s_and_b64 vcc, exec, s[50:51]
	s_cbranch_vccz .LBB0_689
	s_barrier

; #define PG8_STAGE(bufoff, gbase, voff) do { _Pragma("unroll") for (int _i = 0; _i < 2; ++_i) \
;         __builtin_amdgcn_global_load_lds((const unsigned*)((const char*)(gbase) + (voff)[_i]), (PG8_LAS unsigned*)(lds + (bufoff) + ldsw + _i * 8192), 16, 0, 0); } while (0)
; #define PG8_LDA(dst, b, h) do { _Pragma("unroll") for (int m = 0; m < 4; ++m) _Pragma("unroll") for (int k = 0; k < 2; ++k) dst[m][k] = *(const PG8_LAS bf16x8*)(lds + PG8_SA(b, h) + aoff + m * 2048 + k * 1024); } while (0)
; #define PG8_LDB(dst, b, h) do { _Pragma("unroll") for (int n = 0; n < 2; ++n) _Pragma("unroll") for (int k = 0; k < 2; ++k) dst[n][k] = *(const PG8_LAS bf16x8*)(lds + PG8_SB(b, h) + boff + n * 2048 + k * 1024); } while (0)
; #define PG8_MMA(ai, bj, At, Bt) do { __builtin_amdgcn_s_setprio(1); _Pragma("unroll") for (int m = 0; m < 4; ++m) _Pragma("unroll") for (int n = 0; n < 2; ++n) _Pragma("unroll") for (int k = 0; k < 2; ++k) \
;         acc[ai][bj][m][n] = __builtin_amdgcn_mfma_f32_16x16x32_bf16(Bt[n][k], At[m][k], acc[ai][bj][m][n], 0, 0, 0); __builtin_amdgcn_s_setprio(0); } while (0)
; #define PG8_WAIT_V(n) asm volatile("s_waitcnt vmcnt(" #n ")" ::: "memory")
; #define PG8_WAIT_L(n) asm volatile("s_waitcnt lgkmcnt(" #n ")" ::: "memory")
; template <class Epi, class Sched, bool ALIGN_EPI = false, bool SP2 = false>
; __device__ __forceinline__ void gemm_phase(PG8_LAS unsigned char* lds, const Gemm g, const Sched& S, const Epi& E) {
;     ...
;             const bool last = (t == nt - 2);
;             const char* a1 = cA + (size_t)(t + 1) * kstep;
;             const char* a2 = last ? nA : cA + (size_t)(t + 2) * kstep; const char* b2 = last ? nB : cB + (size_t)(t + 2) * kstep;
;             const char* a3 = a2 + kstep; const char* b3 = b2 + kstep;
;             if (last && has_next) S.a_ready(nxt);
;             if constexpr (SP2) {
;             PG8_LDB(B0, 0, 0); PG8_LDB(B1, 0, 1); PG8_SCHED; PG8_LDA(At, 0, 0); PG8_STAGE(PG8_SA(1, 1), a1 + hstep, voffA);
;             PG8_WAIT_V(8); PG8_WAIT_L(0); PG8_BAR; PG8_MMA(0, 0, At, B0); PG8_MMA(0, 1, At, B1); PG8_BAR; PG8_SCHED;
;             PG8_LDA(At, 0, 1); PG8_STAGE(PG8_SB(0, 0), b2, voffB); PG8_STAGE(PG8_SB(0, 1), b2 + hstep, voffB); PG8_STAGE(PG8_SA(0, 0), a2, voffA);
;             PG8_WAIT_V(8); PG8_WAIT_L(0); PG8_BAR; PG8_MMA(1, 0, At, B0); PG8_MMA(1, 1, At, B1); PG8_BAR; PG8_SCHED;
.LBB0_758:
	s_add_u32 s18, s16, 0x100
	s_addc_u32 s19, s17, 0
	s_add_i32 s10, 0, 0x10000
	s_cmpk_eq_i32 s22, 0x7c
	s_cselect_b32 s27, s5, s19
	s_cselect_b32 s26, s7, s18
	s_cselect_b32 s25, s8, s15
	s_cselect_b32 s24, s9, s14
	s_add_i32 s12, 0, 0x14000
	v_add_u32_e32 v160, s10, v216
	v_add_u32_e32 v176, s12, v216
	ds_read_b128 v[148:151], v160
	ds_read_b128 v[152:155], v160 offset:1024
	ds_read_b128 v[156:159], v160 offset:2048
	ds_read_b128 v[160:163], v160 offset:3072
	ds_read_b128 v[164:167], v176
	ds_read_b128 v[168:171], v176 offset:1024
	ds_read_b128 v[172:175], v176 offset:2048
	ds_read_b128 v[176:179], v176 offset:3072
	v_lshl_add_u64 v[200:201], s[16:17], 0, v[144:145]
	s_add_i32 m0, s64, 0xc000
	ds_read_b128 v[180:183], v218
	ds_read_b128 v[184:187], v218 offset:1024
	ds_read_b128 v[188:191], v218 offset:2048
	ds_read_b128 v[192:195], v218 offset:3072
	ds_read_b128 v[196:199], v218 offset:4096
	ds_read_b128 v[220:223], v218 offset:5120
	ds_read_b128 v[224:227], v218 offset:6144
	ds_read_b128 v[228:231], v218 offset:7168
	global_load_lds_dwordx4 v[200:201], off
	v_lshl_add_u64 v[200:201], s[16:17], 0, v[146:147]
	s_add_i32 m0, s64, 0xe000
	s_nop 0
	global_load_lds_dwordx4 v[200:201], off
	s_waitcnt vmcnt(8)
	s_waitcnt lgkmcnt(0)
	s_setprio 0
	s_barrier
	v_mfma_f32_16x16x32_bf16 v[126:129], v[148:151], v[180:183], v[126:129]
	v_mfma_f32_16x16x32_bf16 v[122:125], v[156:159], v[180:183], v[122:125]
	v_mfma_f32_16x16x32_bf16 v[110:113], v[148:151], v[188:191], v[110:113]
	v_mfma_f32_16x16x32_bf16 v[106:109], v[156:159], v[188:191], v[106:109]
	v_mfma_f32_16x16x32_bf16 v[94:97], v[148:151], v[196:199], v[94:97]
	v_mfma_f32_16x16x32_bf16 v[90:93], v[156:159], v[196:199], v[90:93]
	v_mfma_f32_16x16x32_bf16 v[78:81], v[148:151], v[224:227], v[78:81]
	v_mfma_f32_16x16x32_bf16 v[74:77], v[156:159], v[224:227], v[74:77]
	v_mfma_f32_16x16x32_bf16 v[126:129], v[152:155], v[184:187], v[126:129]
	v_mfma_f32_16x16x32_bf16 v[122:125], v[160:163], v[184:187], v[122:125]
	v_mfma_f32_16x16x32_bf16 v[110:113], v[152:155], v[192:195], v[110:113]
	v_mfma_f32_16x16x32_bf16 v[106:109], v[160:163], v[192:195], v[106:109]
	v_mfma_f32_16x16x32_bf16 v[94:97], v[152:155], v[220:223], v[94:97]
	v_mfma_f32_16x16x32_bf16 v[90:93], v[160:163], v[220:223], v[90:93]
	v_mfma_f32_16x16x32_bf16 v[78:81], v[152:155], v[228:231], v[78:81]
	v_mfma_f32_16x16x32_bf16 v[74:77], v[160:163], v[228:231], v[74:77]
	v_mfma_f32_16x16x32_bf16 v[118:121], v[164:167], v[180:183], v[118:121]
	v_mfma_f32_16x16x32_bf16 v[114:117], v[172:175], v[180:183], v[114:117]
	v_mfma_f32_16x16x32_bf16 v[102:105], v[164:167], v[188:191], v[102:105]
	v_mfma_f32_16x16x32_bf16 v[98:101], v[172:175], v[188:191], v[98:101]
	v_mfma_f32_16x16x32_bf16 v[86:89], v[164:167], v[196:199], v[86:89]
	v_mfma_f32_16x16x32_bf16 v[82:85], v[172:175], v[196:199], v[82:85]
	v_mfma_f32_16x16x32_bf16 v[70:73], v[164:167], v[224:227], v[70:73]
	v_mfma_f32_16x16x32_bf16 v[66:69], v[172:175], v[224:227], v[66:69]
	v_mfma_f32_16x16x32_bf16 v[118:121], v[168:171], v[184:187], v[118:121]
	v_mfma_f32_16x16x32_bf16 v[114:117], v[176:179], v[184:187], v[114:117]
	v_mfma_f32_16x16x32_bf16 v[102:105], v[168:171], v[192:195], v[102:105]
	v_mfma_f32_16x16x32_bf16 v[98:101], v[176:179], v[192:195], v[98:101]
	v_mfma_f32_16x16x32_bf16 v[86:89], v[168:171], v[220:223], v[86:89]
	v_mfma_f32_16x16x32_bf16 v[82:85], v[176:179], v[220:223], v[82:85]
	v_mfma_f32_16x16x32_bf16 v[70:73], v[168:171], v[228:231], v[70:73]
	v_mfma_f32_16x16x32_bf16 v[66:69], v[176:179], v[228:231], v[66:69]
	s_barrier
	s_setprio 1
	s_add_i32 s10, s10, s63
	v_lshl_add_u64 v[200:201], s[24:25], 0, v[0:1]
	s_mov_b32 m0, s10
	ds_read_b128 v[180:183], v218 offset:16384
	ds_read_b128 v[184:187], v218 offset:17408
	ds_read_b128 v[188:191], v218 offset:18432
	ds_read_b128 v[192:195], v218 offset:19456
	ds_read_b128 v[196:199], v218 offset:20480
	ds_read_b128 v[220:223], v218 offset:21504
	ds_read_b128 v[224:227], v218 offset:22528
	ds_read_b128 v[228:231], v218 offset:23552
	global_load_lds_dwordx4 v[200:201], off
	s_add_i32 m0, s10, 0x2000
	s_add_u32 s10, s24, 0x200000
	v_lshl_add_u64 v[232:233], s[24:25], 0, v[142:143]
	s_addc_u32 s11, s25, 0
	s_add_i32 s12, s12, s63
	global_load_lds_dwordx4 v[232:233], off
	v_lshl_add_u64 v[234:235], s[10:11], 0, v[0:1]
	s_mov_b32 m0, s12
	v_lshl_add_u64 v[236:237], s[26:27], 0, v[142:143]
	global_load_lds_dwordx4 v[234:235], off
	v_lshl_add_u64 v[234:235], s[10:11], 0, v[142:143]
	s_add_i32 m0, s12, 0x2000
	s_nop 0
	global_load_lds_dwordx4 v[234:235], off
	v_lshl_add_u64 v[234:235], s[26:27], 0, v[0:1]
	s_mov_b32 m0, s64
	s_nop 0
	global_load_lds_dwordx4 v[234:235], off
	s_mov_b32 m0, s65
	s_nop 0
	global_load_lds_dwordx4 v[236:237], off
	s_waitcnt vmcnt(8)
	s_waitcnt lgkmcnt(0)
	s_setprio 0
	s_barrier
; #define PG8_STAGE(bufoff, gbase, voff) do { _Pragma("unroll") for (int _i = 0; _i < 2; ++_i) \
;         __builtin_amdgcn_global_load_lds((const unsigned*)((const char*)(gbase) + (voff)[_i]), (PG8_LAS unsigned*)(lds + (bufoff) + ldsw + _i * 8192), 16, 0, 0); } while (0)
; #define PG8_LDA(dst, b, h) do { _Pragma("unroll") for (int m = 0; m < 4; ++m) _Pragma("unroll") for (int k = 0; k < 2; ++k) dst[m][k] = *(const PG8_LAS bf16x8*)(lds + PG8_SA(b, h) + aoff + m * 2048 + k * 1024); } while (0)
; #define PG8_LDB(dst, b, h) do { _Pragma("unroll") for (int n = 0; n < 2; ++n) _Pragma("unroll") for (int k = 0; k < 2; ++k) dst[n][k] = *(const PG8_LAS bf16x8*)(lds + PG8_SB(b, h) + boff + n * 2048 + k * 1024); } while (0)
; #define PG8_MMA(ai, bj, At, Bt) do { __builtin_amdgcn_s_setprio(1); _Pragma("unroll") for (int m = 0; m < 4; ++m) _Pragma("unroll") for (int n = 0; n < 2; ++n) _Pragma("unroll") for (int k = 0; k < 2; ++k) \
;         acc[ai][bj][m][n] = __builtin_amdgcn_mfma_f32_16x16x32_bf16(Bt[n][k], At[m][k], acc[ai][bj][m][n], 0, 0, 0); __builtin_amdgcn_s_setprio(0); } while (0)
; #define PG8_WAIT_V(n) asm volatile("s_waitcnt vmcnt(" #n ")" ::: "memory")
; #define PG8_WAIT_L(n) asm volatile("s_waitcnt lgkmcnt(" #n ")" ::: "memory")
; #define PG8_BAR __builtin_amdgcn_s_barrier()
; #define PG8_SCHED __builtin_amdgcn_sched_barrier(0)
; template <class Epi, class Sched, bool ALIGN_EPI = false, bool SP2 = false>
; __device__ __forceinline__ void gemm_phase(PG8_LAS unsigned char* lds, const Gemm g, const Sched& S, const Epi& E) {
;     ...
;             PG8_WAIT_V(8); PG8_WAIT_L(0); PG8_BAR; PG8_MMA(1, 0, At, B0); PG8_MMA(1, 1, At, B1); PG8_BAR; PG8_SCHED;
;             PG8_LDB(B0, 1, 0); PG8_LDB(B1, 1, 1); PG8_SCHED; PG8_LDA(At, 1, 0); PG8_STAGE(PG8_SA(0, 1), a2 + hstep, voffA);
;             PG8_WAIT_V(8); PG8_WAIT_L(0); PG8_BAR; PG8_MMA(0, 0, At, B0); PG8_MMA(0, 1, At, B1); PG8_BAR; PG8_SCHED;
	v_mfma_f32_16x16x32_bf16 v[62:65], v[148:151], v[180:183], v[62:65]
	v_mfma_f32_16x16x32_bf16 v[58:61], v[156:159], v[180:183], v[58:61]
	v_mfma_f32_16x16x32_bf16 v[46:49], v[148:151], v[188:191], v[46:49]
	v_mfma_f32_16x16x32_bf16 v[42:45], v[156:159], v[188:191], v[42:45]
	v_mfma_f32_16x16x32_bf16 v[30:33], v[148:151], v[196:199], v[30:33]
	v_mfma_f32_16x16x32_bf16 v[26:29], v[156:159], v[196:199], v[26:29]
	v_mfma_f32_16x16x32_bf16 v[14:17], v[148:151], v[224:227], v[14:17]
	v_mfma_f32_16x16x32_bf16 v[10:13], v[156:159], v[224:227], v[10:13]
	v_mfma_f32_16x16x32_bf16 v[62:65], v[152:155], v[184:187], v[62:65]
	v_mfma_f32_16x16x32_bf16 v[58:61], v[160:163], v[184:187], v[58:61]
	v_mfma_f32_16x16x32_bf16 v[46:49], v[152:155], v[192:195], v[46:49]
	v_mfma_f32_16x16x32_bf16 v[42:45], v[160:163], v[192:195], v[42:45]
	v_mfma_f32_16x16x32_bf16 v[30:33], v[152:155], v[220:223], v[30:33]
	v_mfma_f32_16x16x32_bf16 v[26:29], v[160:163], v[220:223], v[26:29]
	v_mfma_f32_16x16x32_bf16 v[14:17], v[152:155], v[228:231], v[14:17]
	v_mfma_f32_16x16x32_bf16 v[10:13], v[160:163], v[228:231], v[10:13]
	v_mfma_f32_16x16x32_bf16 v[54:57], v[164:167], v[180:183], v[54:57]
	v_mfma_f32_16x16x32_bf16 v[50:53], v[172:175], v[180:183], v[50:53]
	v_mfma_f32_16x16x32_bf16 v[38:41], v[164:167], v[188:191], v[38:41]
	v_mfma_f32_16x16x32_bf16 v[34:37], v[172:175], v[188:191], v[34:37]
	v_mfma_f32_16x16x32_bf16 v[22:25], v[164:167], v[196:199], v[22:25]
	v_mfma_f32_16x16x32_bf16 v[18:21], v[172:175], v[196:199], v[18:21]
	v_mfma_f32_16x16x32_bf16 v[6:9], v[164:167], v[224:227], v[6:9]
	v_mfma_f32_16x16x32_bf16 v[2:5], v[172:175], v[224:227], v[2:5]
	v_mfma_f32_16x16x32_bf16 v[54:57], v[168:171], v[184:187], v[54:57]
	v_mfma_f32_16x16x32_bf16 v[50:53], v[176:179], v[184:187], v[50:53]
	v_mfma_f32_16x16x32_bf16 v[38:41], v[168:171], v[192:195], v[38:41]
	v_mfma_f32_16x16x32_bf16 v[34:37], v[176:179], v[192:195], v[34:37]
	v_mfma_f32_16x16x32_bf16 v[22:25], v[168:171], v[220:223], v[22:25]
	v_mfma_f32_16x16x32_bf16 v[18:21], v[176:179], v[220:223], v[18:21]
	v_mfma_f32_16x16x32_bf16 v[6:9], v[168:171], v[228:231], v[6:9]
	v_mfma_f32_16x16x32_bf16 v[2:5], v[176:179], v[228:231], v[2:5]
	s_barrier
	s_setprio 1
	s_add_i32 s12, 0, 0x18000
	s_add_i32 s13, 0, 0x1c000
	v_add_u32_e32 v160, s12, v216
	v_add_u32_e32 v176, s13, v216
	ds_read_b128 v[148:151], v160
	ds_read_b128 v[152:155], v160 offset:1024
	ds_read_b128 v[156:159], v160 offset:2048
	ds_read_b128 v[160:163], v160 offset:3072
	ds_read_b128 v[164:167], v176
	ds_read_b128 v[168:171], v176 offset:1024
	ds_read_b128 v[172:175], v176 offset:2048
	ds_read_b128 v[176:179], v176 offset:3072
	s_add_u32 s10, s26, 0x200000
	s_addc_u32 s11, s27, 0
	s_mov_b32 m0, s66
	v_lshl_add_u64 v[238:239], s[10:11], 0, v[0:1]
	ds_read_b128 v[180:183], v218 offset:32768
	ds_read_b128 v[184:187], v218 offset:33792
	ds_read_b128 v[188:191], v218 offset:34816
	ds_read_b128 v[192:195], v218 offset:35840
	ds_read_b128 v[196:199], v218 offset:36864
	ds_read_b128 v[220:223], v218 offset:37888
	ds_read_b128 v[224:227], v218 offset:38912
	ds_read_b128 v[228:231], v218 offset:39936
	global_load_lds_dwordx4 v[238:239], off
	v_lshl_add_u64 v[238:239], s[10:11], 0, v[142:143]
	s_mov_b32 m0, s67
	s_nop 0
	global_load_lds_dwordx4 v[238:239], off
	s_waitcnt vmcnt(8)
	s_waitcnt lgkmcnt(0)
	s_setprio 0
	s_barrier
	v_mfma_f32_16x16x32_bf16 v[126:129], v[148:151], v[180:183], v[126:129]
	v_mfma_f32_16x16x32_bf16 v[122:125], v[156:159], v[180:183], v[122:125]
	v_mfma_f32_16x16x32_bf16 v[110:113], v[148:151], v[188:191], v[110:113]
	v_mfma_f32_16x16x32_bf16 v[106:109], v[156:159], v[188:191], v[106:109]
	v_mfma_f32_16x16x32_bf16 v[94:97], v[148:151], v[196:199], v[94:97]
	v_mfma_f32_16x16x32_bf16 v[90:93], v[156:159], v[196:199], v[90:93]
	v_mfma_f32_16x16x32_bf16 v[78:81], v[148:151], v[224:227], v[78:81]
	v_mfma_f32_16x16x32_bf16 v[74:77], v[156:159], v[224:227], v[74:77]
	v_mfma_f32_16x16x32_bf16 v[126:129], v[152:155], v[184:187], v[126:129]
	v_mfma_f32_16x16x32_bf16 v[122:125], v[160:163], v[184:187], v[122:125]
	v_mfma_f32_16x16x32_bf16 v[110:113], v[152:155], v[192:195], v[110:113]
	v_mfma_f32_16x16x32_bf16 v[106:109], v[160:163], v[192:195], v[106:109]
	v_mfma_f32_16x16x32_bf16 v[94:97], v[152:155], v[220:223], v[94:97]
	v_mfma_f32_16x16x32_bf16 v[90:93], v[160:163], v[220:223], v[90:93]
	v_mfma_f32_16x16x32_bf16 v[78:81], v[152:155], v[228:231], v[78:81]
	v_mfma_f32_16x16x32_bf16 v[74:77], v[160:163], v[228:231], v[74:77]
	v_mfma_f32_16x16x32_bf16 v[118:121], v[164:167], v[180:183], v[118:121]
	v_mfma_f32_16x16x32_bf16 v[114:117], v[172:175], v[180:183], v[114:117]
	v_mfma_f32_16x16x32_bf16 v[102:105], v[164:167], v[188:191], v[102:105]
	v_mfma_f32_16x16x32_bf16 v[98:101], v[172:175], v[188:191], v[98:101]
	v_mfma_f32_16x16x32_bf16 v[86:89], v[164:167], v[196:199], v[86:89]
	v_mfma_f32_16x16x32_bf16 v[82:85], v[172:175], v[196:199], v[82:85]
	v_mfma_f32_16x16x32_bf16 v[70:73], v[164:167], v[224:227], v[70:73]
	v_mfma_f32_16x16x32_bf16 v[66:69], v[172:175], v[224:227], v[66:69]
	v_mfma_f32_16x16x32_bf16 v[118:121], v[168:171], v[184:187], v[118:121]
	v_mfma_f32_16x16x32_bf16 v[114:117], v[176:179], v[184:187], v[114:117]
	v_mfma_f32_16x16x32_bf16 v[102:105], v[168:171], v[192:195], v[102:105]
	v_mfma_f32_16x16x32_bf16 v[98:101], v[176:179], v[192:195], v[98:101]
	v_mfma_f32_16x16x32_bf16 v[86:89], v[168:171], v[220:223], v[86:89]
	v_mfma_f32_16x16x32_bf16 v[82:85], v[176:179], v[220:223], v[82:85]
	v_mfma_f32_16x16x32_bf16 v[70:73], v[168:171], v[228:231], v[70:73]
	v_mfma_f32_16x16x32_bf16 v[66:69], v[176:179], v[228:231], v[66:69]
	s_barrier
; #define PG8_STAGE(bufoff, gbase, voff) do { _Pragma("unroll") for (int _i = 0; _i < 2; ++_i) \
;         __builtin_amdgcn_global_load_lds((const unsigned*)((const char*)(gbase) + (voff)[_i]), (PG8_LAS unsigned*)(lds + (bufoff) + ldsw + _i * 8192), 16, 0, 0); } while (0)
; #define PG8_LDA(dst, b, h) do { _Pragma("unroll") for (int m = 0; m < 4; ++m) _Pragma("unroll") for (int k = 0; k < 2; ++k) dst[m][k] = *(const PG8_LAS bf16x8*)(lds + PG8_SA(b, h) + aoff + m * 2048 + k * 1024); } while (0)
; #define PG8_WAIT_V(n) asm volatile("s_waitcnt vmcnt(" #n ")" ::: "memory")
; #define PG8_WAIT_L(n) asm volatile("s_waitcnt lgkmcnt(" #n ")" ::: "memory")
;     __device__ __forceinline__ void operator()(const f32x4 (&acc)[2][2][4][2], const Unit& u, int wr, int wc, int fr, int fq) const {
;     ...
;             for (int m = 0; m < 4; ++m) { const size_t off = (size_t)(row0 + ai * HALF + m * 16) * ldc + col0;
; #pragma unroll
;                 for (int bj = 0; bj < 2; ++bj)
; #pragma unroll
;                     for (int n = 0; n < 2; ++n) bv[m][bj][n] = *(const u32x2*)(xb + off + bj * HALF + n * 16); }
;             asm volatile("" ::: "memory");
; #pragma unroll
;             for (int m = 0; m < 4; ++m) {
;                 const int row = row0 + ai * HALF + m * 16;
;                 const size_t off = (size_t)row * ldc + col0;
;                 float s = 0.f;
; #pragma unroll
;                 for (int bj = 0; bj < 2; ++bj)
; #pragma unroll
;                     for (int n = 0; n < 2; ++n) {
;                         const size_t c = off + bj * HALF + n * 16;
;                         const u32x2 w0 = bv[m][bj][n];
;                         const f32x4 b = {__uint_as_float(w0.x << 16), __uint_as_float(w0.x & 0xffff0000u), __uint_as_float(w0.y << 16), __uint_as_float(w0.y & 0xffff0000u)};
;                         const f32x4 o = b + acc[ai][bj][m][n];
;                         if (fin) { *(f32x4*)(outf + c) = o; }
; template <class Epi, class Sched, bool ALIGN_EPI = false, bool SP2 = false>
; __device__ __forceinline__ void gemm_phase(PG8_LAS unsigned char* lds, const Gemm g, const Sched& S, const Epi& E) {
;     ...
;             PG8_LDA(At, 1, 1); PG8_STAGE(PG8_SB(1, 0), b3, voffB); PG8_STAGE(PG8_SB(1, 1), b3 + hstep, voffB); PG8_STAGE(PG8_SA(1, 0), a3, voffA);
;             PG8_WAIT_V(8); PG8_WAIT_L(0); PG8_BAR; PG8_MMA(1, 0, At, B0); PG8_MMA(1, 1, At, B1); PG8_BAR; PG8_SCHED;
	s_setprio 1
	s_add_i32 s10, s12, s63
	v_lshl_add_u64 v[200:201], v[200:201], 0, s[30:31]
	s_mov_b32 m0, s10
	ds_read_b128 v[180:183], v218 offset:49152
	ds_read_b128 v[184:187], v218 offset:50176
	ds_read_b128 v[188:191], v218 offset:51200
	ds_read_b128 v[192:195], v218 offset:52224
	ds_read_b128 v[196:199], v218 offset:53248
	ds_read_b128 v[220:223], v218 offset:54272
	ds_read_b128 v[224:227], v218 offset:55296
	ds_read_b128 v[228:231], v218 offset:56320
	global_load_lds_dwordx4 v[200:201], off
	s_add_i32 m0, s10, 0x2000
	s_add_u32 s10, s24, 0x200080
	v_lshl_add_u64 v[200:201], v[232:233], 0, s[30:31]
	s_addc_u32 s11, s25, 0
	s_add_i32 s12, s13, s63
	global_load_lds_dwordx4 v[200:201], off
	v_lshl_add_u64 v[200:201], s[10:11], 0, v[0:1]
	s_mov_b32 m0, s12
	s_nop 0
	global_load_lds_dwordx4 v[200:201], off
	v_lshl_add_u64 v[200:201], s[10:11], 0, v[142:143]
	s_add_i32 m0, s12, 0x2000
	s_nop 0
	global_load_lds_dwordx4 v[200:201], off
	v_lshl_add_u64 v[200:201], v[234:235], 0, s[30:31]
	s_mov_b32 m0, s68
	s_nop 0
	global_load_lds_dwordx4 v[200:201], off
	v_lshl_add_u64 v[200:201], v[236:237], 0, s[30:31]
	s_mov_b32 m0, s69
	s_nop 0
	global_load_lds_dwordx4 v[200:201], off
	s_waitcnt vmcnt(8)
	s_waitcnt lgkmcnt(0)
	s_setprio 0
	s_barrier
	v_mfma_f32_16x16x32_bf16 v[62:65], v[148:151], v[180:183], v[62:65]
	v_mfma_f32_16x16x32_bf16 v[58:61], v[156:159], v[180:183], v[58:61]
	v_mfma_f32_16x16x32_bf16 v[46:49], v[148:151], v[188:191], v[46:49]
	v_mfma_f32_16x16x32_bf16 v[42:45], v[156:159], v[188:191], v[42:45]
	v_mfma_f32_16x16x32_bf16 v[30:33], v[148:151], v[196:199], v[30:33]
	v_mfma_f32_16x16x32_bf16 v[26:29], v[156:159], v[196:199], v[26:29]
	v_mfma_f32_16x16x32_bf16 v[14:17], v[148:151], v[224:227], v[14:17]
	v_mfma_f32_16x16x32_bf16 v[10:13], v[156:159], v[224:227], v[10:13]
	v_mfma_f32_16x16x32_bf16 v[62:65], v[152:155], v[184:187], v[62:65]
	v_mfma_f32_16x16x32_bf16 v[58:61], v[160:163], v[184:187], v[58:61]
	v_mfma_f32_16x16x32_bf16 v[46:49], v[152:155], v[192:195], v[46:49]
	v_mfma_f32_16x16x32_bf16 v[42:45], v[160:163], v[192:195], v[42:45]
	v_mfma_f32_16x16x32_bf16 v[30:33], v[152:155], v[220:223], v[30:33]
	v_mfma_f32_16x16x32_bf16 v[26:29], v[160:163], v[220:223], v[26:29]
	v_mfma_f32_16x16x32_bf16 v[14:17], v[152:155], v[228:231], v[14:17]
	v_mfma_f32_16x16x32_bf16 v[10:13], v[160:163], v[228:231], v[10:13]
	v_mfma_f32_16x16x32_bf16 v[54:57], v[164:167], v[180:183], v[54:57]
	v_mfma_f32_16x16x32_bf16 v[50:53], v[172:175], v[180:183], v[50:53]
	v_mfma_f32_16x16x32_bf16 v[38:41], v[164:167], v[188:191], v[38:41]
	v_mfma_f32_16x16x32_bf16 v[34:37], v[172:175], v[188:191], v[34:37]
	v_mfma_f32_16x16x32_bf16 v[22:25], v[164:167], v[196:199], v[22:25]
	v_mfma_f32_16x16x32_bf16 v[18:21], v[172:175], v[196:199], v[18:21]
	v_mfma_f32_16x16x32_bf16 v[6:9], v[164:167], v[224:227], v[6:9]
	v_mfma_f32_16x16x32_bf16 v[2:5], v[172:175], v[224:227], v[2:5]
	v_mfma_f32_16x16x32_bf16 v[54:57], v[168:171], v[184:187], v[54:57]
	v_mfma_f32_16x16x32_bf16 v[50:53], v[176:179], v[184:187], v[50:53]
	v_mfma_f32_16x16x32_bf16 v[38:41], v[168:171], v[192:195], v[38:41]
	v_mfma_f32_16x16x32_bf16 v[34:37], v[176:179], v[192:195], v[34:37]
	v_mfma_f32_16x16x32_bf16 v[22:25], v[168:171], v[220:223], v[22:25]
	v_mfma_f32_16x16x32_bf16 v[18:21], v[176:179], v[220:223], v[18:21]
	v_mfma_f32_16x16x32_bf16 v[6:9], v[168:171], v[228:231], v[6:9]
	v_mfma_f32_16x16x32_bf16 v[2:5], v[176:179], v[228:231], v[2:5]
	s_barrier
	s_setprio 1
	s_add_i32 s22, s22, 2
	s_add_u32 s14, s14, 0x100
	s_addc_u32 s15, s15, 0
	s_cmpk_gt_u32 s22, 0x7d
	s_mov_b64 s[16:17], s[18:19]
	s_cbranch_scc0 .LBB0_758
	v_lshl_add_u32 v152, s4, 8, v215
	v_lshl_or_b32 v148, s2, 8, v217
	v_ashrrev_i32_e32 v149, 31, v148
	v_ashrrev_i32_e32 v153, 31, v152
	v_or_b32_e32 v176, 16, v152
	v_lshl_add_u64 v[150:151], v[148:149], 1, s[50:51]
	v_lshlrev_b64 v[154:155], 12, v[152:153]
	v_ashrrev_i32_e32 v177, 31, v176
	v_or_b32_e32 v164, 32, v152
	v_lshl_add_u64 v[198:199], v[150:151], 0, v[154:155]
	v_lshlrev_b64 v[154:155], 12, v[176:177]
	v_ashrrev_i32_e32 v165, 31, v164
	v_lshl_add_u64 v[186:187], v[150:151], 0, v[154:155]
	v_lshlrev_b64 v[154:155], 12, v[164:165]
	v_lshl_add_u64 v[174:175], v[150:151], 0, v[154:155]
	v_or_b32_e32 v154, 48, v152
	v_ashrrev_i32_e32 v155, 31, v154
	v_lshlrev_b64 v[156:157], 12, v[154:155]
	v_lshl_add_u64 v[162:163], v[150:151], 0, v[156:157]
	global_load_dwordx2 v[192:193], v[198:199], off
	global_load_dwordx2 v[196:197], v[198:199], off offset:32
	global_load_dwordx2 v[194:195], v[198:199], off offset:256
	global_load_dwordx2 v[190:191], v[198:199], off offset:288
	global_load_dwordx2 v[188:189], v[186:187], off
	global_load_dwordx2 v[184:185], v[186:187], off offset:32
	global_load_dwordx2 v[182:183], v[186:187], off offset:256
	global_load_dwordx2 v[180:181], v[186:187], off offset:288
	global_load_dwordx2 v[178:179], v[174:175], off
	global_load_dwordx2 v[172:173], v[174:175], off offset:32
	global_load_dwordx2 v[170:171], v[174:175], off offset:256
	global_load_dwordx2 v[168:169], v[174:175], off offset:288
	global_load_dwordx2 v[166:167], v[162:163], off
	global_load_dwordx2 v[160:161], v[162:163], off offset:32
	global_load_dwordx2 v[158:159], v[162:163], off offset:256
	global_load_dwordx2 v[156:157], v[162:163], off offset:288
	v_readlane_b32 s4, v244, 52
	v_readlane_b32 s5, v244, 53
	s_mov_b64 s[16:17], -1
	s_andn2_b64 vcc, exec, s[4:5]
	v_cndmask_b32_e64 v200, 0, 1, s[4:5]
	v_cmp_ne_u32_e64 s[44:45], 1, v200
	v_lshlrev_b64 v[200:201], 11, v[152:153]
	v_lshl_add_u64 v[200:201], v[200:201], 0, v[148:149]
	s_waitcnt vmcnt(0)
	v_lshlrev_b32_e32 v220, 16, v192
	v_and_b32_e32 v221, 0xffff0000, v192
	v_lshlrev_b32_e32 v192, 16, v193
	v_and_b32_e32 v193, 0xffff0000, v193
	v_pk_add_f32 v[128:129], v[128:129], v[192:193]
	v_pk_add_f32 v[126:127], v[126:127], v[220:221]
	v_lshl_add_u64 v[192:193], v[200:201], 2, s[48:49]
	s_cbranch_vccnz .LBB0_761
	s_mov_b64 s[16:17], 0
	global_store_dwordx4 v[192:193], v[126:129], off
